# ffn_in: ai=0 half of the SwiGLU epilogue hand-written into the load slot of the last K-loop super-phase (overlaps the partner half MFMA block); ai=1 half hand-written after the loop
# speedup vs baseline: 1.0187x; 1.0044x over previous
.LBB0_76:
	s_cmp_eq_u32 s75, 12
	s_cselect_b64 s[46:47], -1, 0
	s_cbranch_scc0 .LBB0_75
	s_and_b64 s[48:49], s[46:47], s[16:17]
	s_andn2_b64 vcc, exec, s[48:49]
	s_cbranch_vccnz .Llast_0
	s_add_i32 m0, s55, 0x21000
	s_nop 0
	global_load_lds_dwordx4 v[144:145], off
.Llast_0:
	v_add_u32_e32 v153, s64, v147
	ds_read_b128 v[160:163], v153
	ds_read_b128 v[164:167], v153 offset:1024
	ds_read_b128 v[168:171], v153 offset:2048
	ds_read_b128 v[172:175], v153 offset:3072
	v_add_u32_e32 v153, s65, v147
	ds_read_b128 v[176:179], v153
	ds_read_b128 v[180:183], v153 offset:1024
	ds_read_b128 v[186:189], v153 offset:2048
	ds_read_b128 v[190:193], v153 offset:3072
	s_add_u32 s48, s44, 0xfffc0080
	s_addc_u32 s49, s45, -1
	s_and_b64 s[46:47], s[46:47], exec
	s_cselect_b32 s49, s27, s49
	s_cselect_b32 s48, s68, s48
	s_cselect_b32 s47, s69, s74
	s_cselect_b32 s46, s70, s71
	v_lshl_add_u64 v[154:155], s[44:45], 0, v[138:139]
	s_add_i32 m0, s55, 0xc000
	ds_read_b128 v[194:197], v150
	ds_read_b128 v[198:201], v150 offset:1024
	ds_read_b128 v[202:205], v150 offset:2048
	ds_read_b128 v[206:209], v150 offset:3072
	ds_read_b128 v[210:213], v150 offset:4096
	ds_read_b128 v[214:217], v150 offset:5120
	ds_read_b128 v[218:221], v150 offset:6144
	ds_read_b128 v[222:225], v150 offset:7168
	global_load_lds_dwordx4 v[154:155], off
	v_lshl_add_u64 v[154:155], s[44:45], 0, v[136:137]
	s_add_i32 m0, s55, 0xe000
	s_nop 0
	global_load_lds_dwordx4 v[154:155], off
	s_waitcnt vmcnt(8)
	s_waitcnt lgkmcnt(0)
	s_barrier
	s_setprio 1
	s_waitcnt lgkmcnt(0)
	v_mfma_f32_16x16x32_bf16 v[124:127], v[160:163], v[194:197], v[124:127]
	v_mfma_f32_16x16x32_bf16 v[116:119], v[168:171], v[194:197], v[116:119]
	v_mfma_f32_16x16x32_bf16 v[108:111], v[160:163], v[202:205], v[108:111]
	v_mfma_f32_16x16x32_bf16 v[100:103], v[168:171], v[202:205], v[100:103]
	v_mfma_f32_16x16x32_bf16 v[92:95], v[160:163], v[210:213], v[92:95]
	v_mfma_f32_16x16x32_bf16 v[84:87], v[168:171], v[210:213], v[84:87]
	v_mfma_f32_16x16x32_bf16 v[76:79], v[160:163], v[218:221], v[76:79]
	v_mfma_f32_16x16x32_bf16 v[68:71], v[168:171], v[218:221], v[68:71]
	v_mfma_f32_16x16x32_bf16 v[124:127], v[164:167], v[198:201], v[124:127]
	v_mfma_f32_16x16x32_bf16 v[116:119], v[172:175], v[198:201], v[116:119]
	v_mfma_f32_16x16x32_bf16 v[108:111], v[164:167], v[206:209], v[108:111]
	v_mfma_f32_16x16x32_bf16 v[100:103], v[172:175], v[206:209], v[100:103]
	v_mfma_f32_16x16x32_bf16 v[92:95], v[164:167], v[214:217], v[92:95]
	v_mfma_f32_16x16x32_bf16 v[84:87], v[172:175], v[214:217], v[84:87]
	v_mfma_f32_16x16x32_bf16 v[76:79], v[164:167], v[222:225], v[76:79]
	v_mfma_f32_16x16x32_bf16 v[68:71], v[172:175], v[222:225], v[68:71]
	s_setprio 0
	s_setprio 1
	v_mfma_f32_16x16x32_bf16 v[120:123], v[176:179], v[194:197], v[120:123]
	v_mfma_f32_16x16x32_bf16 v[112:115], v[186:189], v[194:197], v[112:115]
	v_mfma_f32_16x16x32_bf16 v[104:107], v[176:179], v[202:205], v[104:107]
	v_mfma_f32_16x16x32_bf16 v[96:99], v[186:189], v[202:205], v[96:99]
	v_mfma_f32_16x16x32_bf16 v[88:91], v[176:179], v[210:213], v[88:91]
	v_mfma_f32_16x16x32_bf16 v[80:83], v[186:189], v[210:213], v[80:83]
	v_mfma_f32_16x16x32_bf16 v[72:75], v[176:179], v[218:221], v[72:75]
	v_mfma_f32_16x16x32_bf16 v[64:67], v[186:189], v[218:221], v[64:67]
	v_mfma_f32_16x16x32_bf16 v[120:123], v[180:183], v[198:201], v[120:123]
	v_mfma_f32_16x16x32_bf16 v[112:115], v[190:193], v[198:201], v[112:115]
	v_mfma_f32_16x16x32_bf16 v[104:107], v[180:183], v[206:209], v[104:107]
	v_mfma_f32_16x16x32_bf16 v[96:99], v[190:193], v[206:209], v[96:99]
	v_mfma_f32_16x16x32_bf16 v[88:91], v[180:183], v[214:217], v[88:91]
	v_mfma_f32_16x16x32_bf16 v[80:83], v[190:193], v[214:217], v[80:83]
	v_mfma_f32_16x16x32_bf16 v[72:75], v[180:183], v[222:225], v[72:75]
	v_mfma_f32_16x16x32_bf16 v[64:67], v[190:193], v[222:225], v[64:67]
	s_setprio 0
	s_barrier
	s_add_i32 s76, s64, s52
	v_lshl_add_u64 v[154:155], s[46:47], 0, v[132:133]
	s_mov_b32 m0, s76
	ds_read_b128 v[194:197], v150 offset:16384
	ds_read_b128 v[198:201], v150 offset:17408
	ds_read_b128 v[202:205], v150 offset:18432
	ds_read_b128 v[206:209], v150 offset:19456
	ds_read_b128 v[210:213], v150 offset:20480
	ds_read_b128 v[214:217], v150 offset:21504
	ds_read_b128 v[218:221], v150 offset:22528
	ds_read_b128 v[222:225], v150 offset:23552
	global_load_lds_dwordx4 v[154:155], off
	s_add_i32 m0, s76, 0x2000
	s_add_u32 s76, s46, 0x40000
	v_lshl_add_u64 v[226:227], s[46:47], 0, v[128:129]
	s_addc_u32 s77, s47, 0
	s_add_i32 s78, s65, s52
	global_load_lds_dwordx4 v[226:227], off
	v_lshl_add_u64 v[228:229], s[76:77], 0, v[132:133]
	s_mov_b32 m0, s78
	v_lshl_add_u64 v[230:231], s[48:49], 0, v[130:131]
	global_load_lds_dwordx4 v[228:229], off
	v_lshl_add_u64 v[228:229], s[76:77], 0, v[128:129]
	s_add_i32 m0, s78, 0x2000
	s_nop 0
	global_load_lds_dwordx4 v[228:229], off
	v_lshl_add_u64 v[228:229], s[48:49], 0, v[134:135]
	s_mov_b32 m0, s55
	s_nop 0
	global_load_lds_dwordx4 v[228:229], off
	s_mov_b32 m0, s56
	s_nop 0
	global_load_lds_dwordx4 v[230:231], off
	s_waitcnt vmcnt(8)
	s_waitcnt lgkmcnt(0)
	s_barrier
	s_setprio 1
	s_waitcnt lgkmcnt(0)
	v_mfma_f32_16x16x32_bf16 v[60:63], v[160:163], v[194:197], v[60:63]
	v_mfma_f32_16x16x32_bf16 v[52:55], v[168:171], v[194:197], v[52:55]
	v_mfma_f32_16x16x32_bf16 v[44:47], v[160:163], v[202:205], v[44:47]
	v_mfma_f32_16x16x32_bf16 v[36:39], v[168:171], v[202:205], v[36:39]
	v_mfma_f32_16x16x32_bf16 v[28:31], v[160:163], v[210:213], v[28:31]
	v_mfma_f32_16x16x32_bf16 v[20:23], v[168:171], v[210:213], v[20:23]
	v_mfma_f32_16x16x32_bf16 v[12:15], v[160:163], v[218:221], v[12:15]
	v_mfma_f32_16x16x32_bf16 v[4:7], v[168:171], v[218:221], v[4:7]
	v_mfma_f32_16x16x32_bf16 v[60:63], v[164:167], v[198:201], v[60:63]
	v_mfma_f32_16x16x32_bf16 v[52:55], v[172:175], v[198:201], v[52:55]
	v_mfma_f32_16x16x32_bf16 v[44:47], v[164:167], v[206:209], v[44:47]
	v_mfma_f32_16x16x32_bf16 v[36:39], v[172:175], v[206:209], v[36:39]
	v_mfma_f32_16x16x32_bf16 v[28:31], v[164:167], v[214:217], v[28:31]
	v_mfma_f32_16x16x32_bf16 v[20:23], v[172:175], v[214:217], v[20:23]
	v_mfma_f32_16x16x32_bf16 v[12:15], v[164:167], v[222:225], v[12:15]
	v_mfma_f32_16x16x32_bf16 v[4:7], v[172:175], v[222:225], v[4:7]
	s_setprio 0
	s_setprio 1
	v_mfma_f32_16x16x32_bf16 v[56:59], v[176:179], v[194:197], v[56:59]
	v_mfma_f32_16x16x32_bf16 v[48:51], v[186:189], v[194:197], v[48:51]
	v_mfma_f32_16x16x32_bf16 v[40:43], v[176:179], v[202:205], v[40:43]
	v_mfma_f32_16x16x32_bf16 v[32:35], v[186:189], v[202:205], v[32:35]
	v_mfma_f32_16x16x32_bf16 v[24:27], v[176:179], v[210:213], v[24:27]
	v_mfma_f32_16x16x32_bf16 v[16:19], v[186:189], v[210:213], v[16:19]
	v_mfma_f32_16x16x32_bf16 v[8:11], v[176:179], v[218:221], v[8:11]
	v_mfma_f32_16x16x32_bf16 v[0:3], v[186:189], v[218:221], v[0:3]
	v_mfma_f32_16x16x32_bf16 v[56:59], v[180:183], v[198:201], v[56:59]
	v_mfma_f32_16x16x32_bf16 v[48:51], v[190:193], v[198:201], v[48:51]
	v_mfma_f32_16x16x32_bf16 v[40:43], v[180:183], v[206:209], v[40:43]
	v_mfma_f32_16x16x32_bf16 v[32:35], v[190:193], v[206:209], v[32:35]
	v_mfma_f32_16x16x32_bf16 v[24:27], v[180:183], v[214:217], v[24:27]
	v_mfma_f32_16x16x32_bf16 v[16:19], v[190:193], v[214:217], v[16:19]
	v_mfma_f32_16x16x32_bf16 v[8:11], v[180:183], v[222:225], v[8:11]
	v_mfma_f32_16x16x32_bf16 v[0:3], v[190:193], v[222:225], v[0:3]
	s_setprio 0
	s_barrier
	s_add_i32 s76, 0, 0x18000
	v_add_u32_e32 v153, s76, v147
	s_add_i32 s77, 0, 0x1c000
	ds_read_b128 v[160:163], v153
	ds_read_b128 v[164:167], v153 offset:1024
	ds_read_b128 v[168:171], v153 offset:2048
	ds_read_b128 v[172:175], v153 offset:3072
	v_add_u32_e32 v153, s77, v147
	ds_read_b128 v[176:179], v153
	ds_read_b128 v[180:183], v153 offset:1024
	ds_read_b128 v[186:189], v153 offset:2048
	ds_read_b128 v[190:193], v153 offset:3072
	s_add_u32 s48, s48, 0x40000
	s_addc_u32 s49, s49, 0
	s_mov_b32 m0, s57
	v_lshl_add_u64 v[232:233], s[48:49], 0, v[134:135]
	ds_read_b128 v[194:197], v150 offset:32768
	ds_read_b128 v[198:201], v150 offset:33792
	ds_read_b128 v[202:205], v150 offset:34816
	ds_read_b128 v[206:209], v150 offset:35840
	ds_read_b128 v[210:213], v150 offset:36864
	ds_read_b128 v[214:217], v150 offset:37888
	ds_read_b128 v[218:221], v150 offset:38912
	ds_read_b128 v[222:225], v150 offset:39936
	global_load_lds_dwordx4 v[232:233], off
	v_lshl_add_u64 v[232:233], s[48:49], 0, v[130:131]
	s_mov_b32 m0, s58
	s_nop 0
	global_load_lds_dwordx4 v[232:233], off
	s_waitcnt vmcnt(8)
	s_waitcnt lgkmcnt(0)
	s_barrier
	s_setprio 1
	s_waitcnt lgkmcnt(0)
	v_mfma_f32_16x16x32_bf16 v[124:127], v[160:163], v[194:197], v[124:127]
	v_mfma_f32_16x16x32_bf16 v[116:119], v[168:171], v[194:197], v[116:119]
	v_mfma_f32_16x16x32_bf16 v[108:111], v[160:163], v[202:205], v[108:111]
	v_mfma_f32_16x16x32_bf16 v[100:103], v[168:171], v[202:205], v[100:103]
	v_mfma_f32_16x16x32_bf16 v[92:95], v[160:163], v[210:213], v[92:95]
	v_mfma_f32_16x16x32_bf16 v[84:87], v[168:171], v[210:213], v[84:87]
	v_mfma_f32_16x16x32_bf16 v[76:79], v[160:163], v[218:221], v[76:79]
	v_mfma_f32_16x16x32_bf16 v[68:71], v[168:171], v[218:221], v[68:71]
	v_mfma_f32_16x16x32_bf16 v[124:127], v[164:167], v[198:201], v[124:127]
	v_mfma_f32_16x16x32_bf16 v[116:119], v[172:175], v[198:201], v[116:119]
	v_mfma_f32_16x16x32_bf16 v[108:111], v[164:167], v[206:209], v[108:111]
	v_mfma_f32_16x16x32_bf16 v[100:103], v[172:175], v[206:209], v[100:103]
	v_mfma_f32_16x16x32_bf16 v[92:95], v[164:167], v[214:217], v[92:95]
	v_mfma_f32_16x16x32_bf16 v[84:87], v[172:175], v[214:217], v[84:87]
	v_mfma_f32_16x16x32_bf16 v[76:79], v[164:167], v[222:225], v[76:79]
	v_mfma_f32_16x16x32_bf16 v[68:71], v[172:175], v[222:225], v[68:71]
	s_setprio 0
	s_setprio 1
	v_mfma_f32_16x16x32_bf16 v[120:123], v[176:179], v[194:197], v[120:123]
	v_mfma_f32_16x16x32_bf16 v[112:115], v[186:189], v[194:197], v[112:115]
	v_mfma_f32_16x16x32_bf16 v[104:107], v[176:179], v[202:205], v[104:107]
	v_mfma_f32_16x16x32_bf16 v[96:99], v[186:189], v[202:205], v[96:99]
	v_mfma_f32_16x16x32_bf16 v[88:91], v[176:179], v[210:213], v[88:91]
	v_mfma_f32_16x16x32_bf16 v[80:83], v[186:189], v[210:213], v[80:83]
	v_mfma_f32_16x16x32_bf16 v[72:75], v[176:179], v[218:221], v[72:75]
	v_mfma_f32_16x16x32_bf16 v[64:67], v[186:189], v[218:221], v[64:67]
	v_mfma_f32_16x16x32_bf16 v[120:123], v[180:183], v[198:201], v[120:123]
	v_mfma_f32_16x16x32_bf16 v[112:115], v[190:193], v[198:201], v[112:115]
	v_mfma_f32_16x16x32_bf16 v[104:107], v[180:183], v[206:209], v[104:107]
	v_mfma_f32_16x16x32_bf16 v[96:99], v[190:193], v[206:209], v[96:99]
	v_mfma_f32_16x16x32_bf16 v[88:91], v[180:183], v[214:217], v[88:91]
	v_mfma_f32_16x16x32_bf16 v[80:83], v[190:193], v[214:217], v[80:83]
	v_mfma_f32_16x16x32_bf16 v[72:75], v[180:183], v[222:225], v[72:75]
	v_mfma_f32_16x16x32_bf16 v[64:67], v[190:193], v[222:225], v[64:67]
	s_setprio 0
	s_barrier
	v_add_u32_e32 v234, 0x21000, v151
	ds_read_b128 v[236:239], v234
	ds_read_b128 v[240:243], v234 offset:256
	ds_read_b128 v[244:247], v234 offset:512
	ds_read_b128 v[248:251], v234 offset:768
	v_add_u32_e32 v235, s23, v146
	v_mul_u32_u24_e32 v235, 0x1600, v235
	v_lshl_or_b32 v234, s67, 7, v149
	v_lshl_add_u32 v235, v234, 1, v235
	s_add_i32 s48, s76, s52
	v_lshl_add_u64 v[154:155], v[154:155], 0, s[14:15]
	s_mov_b32 m0, s48
	ds_read_b128 v[194:197], v150 offset:49152
	ds_read_b128 v[198:201], v150 offset:50176
	ds_read_b128 v[202:205], v150 offset:51200
	ds_read_b128 v[206:209], v150 offset:52224
	ds_read_b128 v[210:213], v150 offset:53248
	ds_read_b128 v[214:217], v150 offset:54272
	ds_read_b128 v[218:221], v150 offset:55296
	ds_read_b128 v[222:225], v150 offset:56320
	global_load_lds_dwordx4 v[154:155], off
	s_add_i32 m0, s48, 0x2000
	s_add_u32 s46, s46, 0x40080
	v_lshl_add_u64 v[154:155], v[226:227], 0, s[14:15]
	s_addc_u32 s47, s47, 0
	s_add_i32 s48, s77, s52
	global_load_lds_dwordx4 v[154:155], off
	v_lshl_add_u64 v[154:155], s[46:47], 0, v[132:133]
	s_mov_b32 m0, s48
	s_nop 0
	global_load_lds_dwordx4 v[154:155], off
	v_lshl_add_u64 v[154:155], s[46:47], 0, v[128:129]
	s_add_i32 m0, s48, 0x2000
	s_nop 0
	global_load_lds_dwordx4 v[154:155], off
	v_lshl_add_u64 v[154:155], v[228:229], 0, s[14:15]
	s_mov_b32 m0, s60
	s_nop 0
	global_load_lds_dwordx4 v[154:155], off
	v_lshl_add_u64 v[154:155], v[230:231], 0, s[14:15]
	s_mov_b32 m0, s61
	s_nop 0
	global_load_lds_dwordx4 v[154:155], off
	s_waitcnt lgkmcnt(8)
	v_add_f32_e32 v236, v236, v237
	v_add_f32_e32 v238, v238, v239
	v_add_f32_e32 v240, v240, v241
	v_add_f32_e32 v242, v242, v243
	v_add_f32_e32 v244, v244, v245
	v_add_f32_e32 v246, v246, v247
	v_add_f32_e32 v248, v248, v249
	v_add_f32_e32 v250, v250, v251
	v_add_f32_e32 v236, v236, v238
	v_add_f32_e32 v240, v240, v242
	v_add_f32_e32 v244, v244, v246
	v_add_f32_e32 v248, v248, v250
	v_fmamk_f32 v236, v236, 0x3a800000, v152
	v_fmamk_f32 v240, v240, 0x3a800000, v152
	v_fmamk_f32 v244, v244, 0x3a800000, v152
	v_fmamk_f32 v248, v248, 0x3a800000, v152
	v_rsq_f32_e32 v236, v236
	v_rsq_f32_e32 v240, v240
	v_rsq_f32_e32 v244, v244
	v_rsq_f32_e32 v248, v248
	v_mul_f32_e32 v252, 0xbfb8aa3b, v236
	v_mul_f32_e32 v254, v236, v236
	v_pk_mul_f32 v[120:121], v[124:125], v[120:121]
	v_pk_mul_f32 v[122:123], v[126:127], v[122:123]
	v_pk_mul_f32 v[112:113], v[116:117], v[112:113]
	v_pk_mul_f32 v[114:115], v[118:119], v[114:115]
	v_pk_mul_f32 v[124:125], v[124:125], v[252:253] op_sel_hi:[1,0]
	v_pk_mul_f32 v[126:127], v[126:127], v[252:253] op_sel_hi:[1,0]
	v_pk_mul_f32 v[116:117], v[116:117], v[252:253] op_sel_hi:[1,0]
	v_pk_mul_f32 v[118:119], v[118:119], v[252:253] op_sel_hi:[1,0]
	v_exp_f32_e32 v124, v124
	v_exp_f32_e32 v125, v125
	v_exp_f32_e32 v126, v126
	v_exp_f32_e32 v127, v127
	v_exp_f32_e32 v116, v116
	v_exp_f32_e32 v117, v117
	v_exp_f32_e32 v118, v118
	v_exp_f32_e32 v119, v119
	v_pk_add_f32 v[124:125], v[124:125], 1.0 op_sel_hi:[1,0]
	v_pk_add_f32 v[126:127], v[126:127], 1.0 op_sel_hi:[1,0]
	v_pk_add_f32 v[116:117], v[116:117], 1.0 op_sel_hi:[1,0]
	v_pk_add_f32 v[118:119], v[118:119], 1.0 op_sel_hi:[1,0]
	v_rcp_f32_e32 v124, v124
	v_rcp_f32_e32 v125, v125
	v_rcp_f32_e32 v126, v126
	v_rcp_f32_e32 v127, v127
	v_rcp_f32_e32 v116, v116
	v_rcp_f32_e32 v117, v117
	v_rcp_f32_e32 v118, v118
	v_rcp_f32_e32 v119, v119
	v_pk_mul_f32 v[120:121], v[120:121], v[254:255] op_sel_hi:[1,0]
	v_pk_mul_f32 v[122:123], v[122:123], v[254:255] op_sel_hi:[1,0]
	v_pk_mul_f32 v[112:113], v[112:113], v[254:255] op_sel_hi:[1,0]
	v_pk_mul_f32 v[114:115], v[114:115], v[254:255] op_sel_hi:[1,0]
	v_pk_mul_f32 v[120:121], v[120:121], v[124:125]
	v_pk_mul_f32 v[122:123], v[122:123], v[126:127]
	v_pk_mul_f32 v[112:113], v[112:113], v[116:117]
	v_pk_mul_f32 v[114:115], v[114:115], v[118:119]
	v_cvt_pk_bf16_f32 v120, v120, v121
	v_cvt_pk_bf16_f32 v121, v122, v123
	v_cvt_pk_bf16_f32 v122, v112, v113
	v_cvt_pk_bf16_f32 v123, v114, v115
	global_store_dwordx4 v235, v[120:123], s[10:11]
	v_add_u32_e32 v234, 0x16000, v235
	v_mul_f32_e32 v252, 0xbfb8aa3b, v240
	v_mul_f32_e32 v254, v240, v240
	v_pk_mul_f32 v[104:105], v[108:109], v[104:105]
	v_pk_mul_f32 v[106:107], v[110:111], v[106:107]
	v_pk_mul_f32 v[96:97], v[100:101], v[96:97]
	v_pk_mul_f32 v[98:99], v[102:103], v[98:99]
	v_pk_mul_f32 v[108:109], v[108:109], v[252:253] op_sel_hi:[1,0]
	v_pk_mul_f32 v[110:111], v[110:111], v[252:253] op_sel_hi:[1,0]
	v_pk_mul_f32 v[100:101], v[100:101], v[252:253] op_sel_hi:[1,0]
	v_pk_mul_f32 v[102:103], v[102:103], v[252:253] op_sel_hi:[1,0]
	v_exp_f32_e32 v108, v108
	v_exp_f32_e32 v109, v109
	v_exp_f32_e32 v110, v110
	v_exp_f32_e32 v111, v111
	v_exp_f32_e32 v100, v100
	v_exp_f32_e32 v101, v101
	v_exp_f32_e32 v102, v102
	v_exp_f32_e32 v103, v103
	v_pk_add_f32 v[108:109], v[108:109], 1.0 op_sel_hi:[1,0]
	v_pk_add_f32 v[110:111], v[110:111], 1.0 op_sel_hi:[1,0]
	v_pk_add_f32 v[100:101], v[100:101], 1.0 op_sel_hi:[1,0]
	v_pk_add_f32 v[102:103], v[102:103], 1.0 op_sel_hi:[1,0]
	v_rcp_f32_e32 v108, v108
	v_rcp_f32_e32 v109, v109
	v_rcp_f32_e32 v110, v110
	v_rcp_f32_e32 v111, v111
	v_rcp_f32_e32 v100, v100
	v_rcp_f32_e32 v101, v101
	v_rcp_f32_e32 v102, v102
	v_rcp_f32_e32 v103, v103
	v_pk_mul_f32 v[104:105], v[104:105], v[254:255] op_sel_hi:[1,0]
	v_pk_mul_f32 v[106:107], v[106:107], v[254:255] op_sel_hi:[1,0]
	v_pk_mul_f32 v[96:97], v[96:97], v[254:255] op_sel_hi:[1,0]
	v_pk_mul_f32 v[98:99], v[98:99], v[254:255] op_sel_hi:[1,0]
	v_pk_mul_f32 v[104:105], v[104:105], v[108:109]
	v_pk_mul_f32 v[106:107], v[106:107], v[110:111]
	v_pk_mul_f32 v[96:97], v[96:97], v[100:101]
	v_pk_mul_f32 v[98:99], v[98:99], v[102:103]
	v_cvt_pk_bf16_f32 v104, v104, v105
	v_cvt_pk_bf16_f32 v105, v106, v107
	v_cvt_pk_bf16_f32 v106, v96, v97
	v_cvt_pk_bf16_f32 v107, v98, v99
	global_store_dwordx4 v234, v[104:107], s[10:11]
	v_add_u32_e32 v235, 0x16000, v234
	v_mul_f32_e32 v252, 0xbfb8aa3b, v244
	v_mul_f32_e32 v254, v244, v244
	v_pk_mul_f32 v[88:89], v[92:93], v[88:89]
	v_pk_mul_f32 v[90:91], v[94:95], v[90:91]
	v_pk_mul_f32 v[80:81], v[84:85], v[80:81]
	v_pk_mul_f32 v[82:83], v[86:87], v[82:83]
	v_pk_mul_f32 v[92:93], v[92:93], v[252:253] op_sel_hi:[1,0]
	v_pk_mul_f32 v[94:95], v[94:95], v[252:253] op_sel_hi:[1,0]
	v_pk_mul_f32 v[84:85], v[84:85], v[252:253] op_sel_hi:[1,0]
	v_pk_mul_f32 v[86:87], v[86:87], v[252:253] op_sel_hi:[1,0]
	v_exp_f32_e32 v92, v92
	v_exp_f32_e32 v93, v93
	v_exp_f32_e32 v94, v94
	v_exp_f32_e32 v95, v95
	v_exp_f32_e32 v84, v84
	v_exp_f32_e32 v85, v85
	v_exp_f32_e32 v86, v86
	v_exp_f32_e32 v87, v87
	v_pk_add_f32 v[92:93], v[92:93], 1.0 op_sel_hi:[1,0]
	v_pk_add_f32 v[94:95], v[94:95], 1.0 op_sel_hi:[1,0]
	v_pk_add_f32 v[84:85], v[84:85], 1.0 op_sel_hi:[1,0]
	v_pk_add_f32 v[86:87], v[86:87], 1.0 op_sel_hi:[1,0]
	v_rcp_f32_e32 v92, v92
	v_rcp_f32_e32 v93, v93
	v_rcp_f32_e32 v94, v94
	v_rcp_f32_e32 v95, v95
	v_rcp_f32_e32 v84, v84
	v_rcp_f32_e32 v85, v85
	v_rcp_f32_e32 v86, v86
	v_rcp_f32_e32 v87, v87
	v_pk_mul_f32 v[88:89], v[88:89], v[254:255] op_sel_hi:[1,0]
	v_pk_mul_f32 v[90:91], v[90:91], v[254:255] op_sel_hi:[1,0]
	v_pk_mul_f32 v[80:81], v[80:81], v[254:255] op_sel_hi:[1,0]
	v_pk_mul_f32 v[82:83], v[82:83], v[254:255] op_sel_hi:[1,0]
	v_pk_mul_f32 v[88:89], v[88:89], v[92:93]
	v_pk_mul_f32 v[90:91], v[90:91], v[94:95]
	v_pk_mul_f32 v[80:81], v[80:81], v[84:85]
	v_pk_mul_f32 v[82:83], v[82:83], v[86:87]
	v_cvt_pk_bf16_f32 v88, v88, v89
	v_cvt_pk_bf16_f32 v89, v90, v91
	v_cvt_pk_bf16_f32 v90, v80, v81
	v_cvt_pk_bf16_f32 v91, v82, v83
	global_store_dwordx4 v235, v[88:91], s[10:11]
	v_add_u32_e32 v234, 0x16000, v235
	v_mul_f32_e32 v252, 0xbfb8aa3b, v248
	v_mul_f32_e32 v254, v248, v248
	v_pk_mul_f32 v[72:73], v[76:77], v[72:73]
	v_pk_mul_f32 v[74:75], v[78:79], v[74:75]
	v_pk_mul_f32 v[64:65], v[68:69], v[64:65]
	v_pk_mul_f32 v[66:67], v[70:71], v[66:67]
	v_pk_mul_f32 v[76:77], v[76:77], v[252:253] op_sel_hi:[1,0]
	v_pk_mul_f32 v[78:79], v[78:79], v[252:253] op_sel_hi:[1,0]
	v_pk_mul_f32 v[68:69], v[68:69], v[252:253] op_sel_hi:[1,0]
	v_pk_mul_f32 v[70:71], v[70:71], v[252:253] op_sel_hi:[1,0]
	v_exp_f32_e32 v76, v76
	v_exp_f32_e32 v77, v77
	v_exp_f32_e32 v78, v78
	v_exp_f32_e32 v79, v79
	v_exp_f32_e32 v68, v68
	v_exp_f32_e32 v69, v69
	v_exp_f32_e32 v70, v70
	v_exp_f32_e32 v71, v71
	v_pk_add_f32 v[76:77], v[76:77], 1.0 op_sel_hi:[1,0]
	v_pk_add_f32 v[78:79], v[78:79], 1.0 op_sel_hi:[1,0]
	v_pk_add_f32 v[68:69], v[68:69], 1.0 op_sel_hi:[1,0]
	v_pk_add_f32 v[70:71], v[70:71], 1.0 op_sel_hi:[1,0]
	v_rcp_f32_e32 v76, v76
	v_rcp_f32_e32 v77, v77
	v_rcp_f32_e32 v78, v78
	v_rcp_f32_e32 v79, v79
	v_rcp_f32_e32 v68, v68
	v_rcp_f32_e32 v69, v69
	v_rcp_f32_e32 v70, v70
	v_rcp_f32_e32 v71, v71
	v_pk_mul_f32 v[72:73], v[72:73], v[254:255] op_sel_hi:[1,0]
	v_pk_mul_f32 v[74:75], v[74:75], v[254:255] op_sel_hi:[1,0]
	v_pk_mul_f32 v[64:65], v[64:65], v[254:255] op_sel_hi:[1,0]
	v_pk_mul_f32 v[66:67], v[66:67], v[254:255] op_sel_hi:[1,0]
	v_pk_mul_f32 v[72:73], v[72:73], v[76:77]
	v_pk_mul_f32 v[74:75], v[74:75], v[78:79]
	v_pk_mul_f32 v[64:65], v[64:65], v[68:69]
	v_pk_mul_f32 v[66:67], v[66:67], v[70:71]
	v_cvt_pk_bf16_f32 v72, v72, v73
	v_cvt_pk_bf16_f32 v73, v74, v75
	v_cvt_pk_bf16_f32 v74, v64, v65
	v_cvt_pk_bf16_f32 v75, v66, v67
	global_store_dwordx4 v234, v[72:75], s[10:11]
	s_waitcnt vmcnt(12)
	s_waitcnt lgkmcnt(0)
	s_barrier
	s_setprio 1
	s_waitcnt lgkmcnt(0)
	v_mfma_f32_16x16x32_bf16 v[60:63], v[160:163], v[194:197], v[60:63]
	v_mfma_f32_16x16x32_bf16 v[52:55], v[168:171], v[194:197], v[52:55]
	v_mfma_f32_16x16x32_bf16 v[44:47], v[160:163], v[202:205], v[44:47]
	v_mfma_f32_16x16x32_bf16 v[36:39], v[168:171], v[202:205], v[36:39]
	v_mfma_f32_16x16x32_bf16 v[28:31], v[160:163], v[210:213], v[28:31]
	v_mfma_f32_16x16x32_bf16 v[20:23], v[168:171], v[210:213], v[20:23]
	v_mfma_f32_16x16x32_bf16 v[12:15], v[160:163], v[218:221], v[12:15]
	v_mfma_f32_16x16x32_bf16 v[4:7], v[168:171], v[218:221], v[4:7]
	v_mfma_f32_16x16x32_bf16 v[60:63], v[164:167], v[198:201], v[60:63]
	v_mfma_f32_16x16x32_bf16 v[52:55], v[172:175], v[198:201], v[52:55]
	v_mfma_f32_16x16x32_bf16 v[44:47], v[164:167], v[206:209], v[44:47]
	v_mfma_f32_16x16x32_bf16 v[36:39], v[172:175], v[206:209], v[36:39]
	v_mfma_f32_16x16x32_bf16 v[28:31], v[164:167], v[214:217], v[28:31]
	v_mfma_f32_16x16x32_bf16 v[20:23], v[172:175], v[214:217], v[20:23]
	v_mfma_f32_16x16x32_bf16 v[12:15], v[164:167], v[222:225], v[12:15]
	v_mfma_f32_16x16x32_bf16 v[4:7], v[172:175], v[222:225], v[4:7]
	s_setprio 0
	s_setprio 1
	v_mfma_f32_16x16x32_bf16 v[56:59], v[176:179], v[194:197], v[56:59]
	v_mfma_f32_16x16x32_bf16 v[48:51], v[186:189], v[194:197], v[48:51]
	v_mfma_f32_16x16x32_bf16 v[40:43], v[176:179], v[202:205], v[40:43]
	v_mfma_f32_16x16x32_bf16 v[32:35], v[186:189], v[202:205], v[32:35]
	v_mfma_f32_16x16x32_bf16 v[24:27], v[176:179], v[210:213], v[24:27]
	v_mfma_f32_16x16x32_bf16 v[16:19], v[186:189], v[210:213], v[16:19]
	v_mfma_f32_16x16x32_bf16 v[8:11], v[176:179], v[218:221], v[8:11]
	v_mfma_f32_16x16x32_bf16 v[0:3], v[186:189], v[218:221], v[0:3]
	v_mfma_f32_16x16x32_bf16 v[56:59], v[180:183], v[198:201], v[56:59]
	v_mfma_f32_16x16x32_bf16 v[48:51], v[190:193], v[198:201], v[48:51]
	v_mfma_f32_16x16x32_bf16 v[40:43], v[180:183], v[206:209], v[40:43]
	v_mfma_f32_16x16x32_bf16 v[32:35], v[190:193], v[206:209], v[32:35]
	v_mfma_f32_16x16x32_bf16 v[24:27], v[180:183], v[214:217], v[24:27]
	v_mfma_f32_16x16x32_bf16 v[16:19], v[190:193], v[214:217], v[16:19]
	v_mfma_f32_16x16x32_bf16 v[8:11], v[180:183], v[222:225], v[8:11]
	v_mfma_f32_16x16x32_bf16 v[0:3], v[190:193], v[222:225], v[0:3]
	s_setprio 0
	s_barrier
	s_add_i32 s75, s75, 2
	s_add_u32 s71, s71, 0x100
	s_addc_u32 s74, s74, 0
	s_add_u32 s44, s44, 0x100
	s_addc_u32 s45, s45, 0

.LBB0_80:
	v_add_u32_e32 v235, 0x84000, v235
	v_add_u32_e32 v234, 0x21800, v151
	ds_read_b128 v[236:239], v234
	ds_read_b128 v[240:243], v234 offset:256
	ds_read_b128 v[244:247], v234 offset:512
	ds_read_b128 v[248:251], v234 offset:768
	s_waitcnt lgkmcnt(0)
	v_add_f32_e32 v236, v236, v237
	v_add_f32_e32 v238, v238, v239
	v_add_f32_e32 v240, v240, v241
	v_add_f32_e32 v242, v242, v243
	v_add_f32_e32 v244, v244, v245
	v_add_f32_e32 v246, v246, v247
	v_add_f32_e32 v248, v248, v249
	v_add_f32_e32 v250, v250, v251
	v_add_f32_e32 v236, v236, v238
	v_add_f32_e32 v240, v240, v242
	v_add_f32_e32 v244, v244, v246
	v_add_f32_e32 v248, v248, v250
	v_fmamk_f32 v236, v236, 0x3a800000, v152
	v_fmamk_f32 v240, v240, 0x3a800000, v152
	v_fmamk_f32 v244, v244, 0x3a800000, v152
	v_fmamk_f32 v248, v248, 0x3a800000, v152
	v_rsq_f32_e32 v236, v236
	v_rsq_f32_e32 v240, v240
	v_rsq_f32_e32 v244, v244
	v_rsq_f32_e32 v248, v248
	v_mul_f32_e32 v252, 0xbfb8aa3b, v236
	v_mul_f32_e32 v254, v236, v236
	v_pk_mul_f32 v[56:57], v[60:61], v[56:57]
	v_pk_mul_f32 v[58:59], v[62:63], v[58:59]
	v_pk_mul_f32 v[48:49], v[52:53], v[48:49]
	v_pk_mul_f32 v[50:51], v[54:55], v[50:51]
	v_pk_mul_f32 v[60:61], v[60:61], v[252:253] op_sel_hi:[1,0]
	v_pk_mul_f32 v[62:63], v[62:63], v[252:253] op_sel_hi:[1,0]
	v_pk_mul_f32 v[52:53], v[52:53], v[252:253] op_sel_hi:[1,0]
	v_pk_mul_f32 v[54:55], v[54:55], v[252:253] op_sel_hi:[1,0]
	v_exp_f32_e32 v60, v60
	v_exp_f32_e32 v61, v61
	v_exp_f32_e32 v62, v62
	v_exp_f32_e32 v63, v63
	v_exp_f32_e32 v52, v52
	v_exp_f32_e32 v53, v53
	v_exp_f32_e32 v54, v54
	v_exp_f32_e32 v55, v55
	v_pk_add_f32 v[60:61], v[60:61], 1.0 op_sel_hi:[1,0]
	v_pk_add_f32 v[62:63], v[62:63], 1.0 op_sel_hi:[1,0]
	v_pk_add_f32 v[52:53], v[52:53], 1.0 op_sel_hi:[1,0]
	v_pk_add_f32 v[54:55], v[54:55], 1.0 op_sel_hi:[1,0]
	v_rcp_f32_e32 v60, v60
	v_rcp_f32_e32 v61, v61
	v_rcp_f32_e32 v62, v62
	v_rcp_f32_e32 v63, v63
	v_rcp_f32_e32 v52, v52
	v_rcp_f32_e32 v53, v53
	v_rcp_f32_e32 v54, v54
	v_rcp_f32_e32 v55, v55
	v_pk_mul_f32 v[56:57], v[56:57], v[254:255] op_sel_hi:[1,0]
	v_pk_mul_f32 v[58:59], v[58:59], v[254:255] op_sel_hi:[1,0]
	v_pk_mul_f32 v[48:49], v[48:49], v[254:255] op_sel_hi:[1,0]
	v_pk_mul_f32 v[50:51], v[50:51], v[254:255] op_sel_hi:[1,0]
	v_pk_mul_f32 v[56:57], v[56:57], v[60:61]
	v_pk_mul_f32 v[58:59], v[58:59], v[62:63]
	v_pk_mul_f32 v[48:49], v[48:49], v[52:53]
	v_pk_mul_f32 v[50:51], v[50:51], v[54:55]
	v_cvt_pk_bf16_f32 v56, v56, v57
	v_cvt_pk_bf16_f32 v57, v58, v59
	v_cvt_pk_bf16_f32 v58, v48, v49
	v_cvt_pk_bf16_f32 v59, v50, v51
	global_store_dwordx4 v235, v[56:59], s[10:11]
	v_add_u32_e32 v234, 0x16000, v235
	v_mul_f32_e32 v252, 0xbfb8aa3b, v240
	v_mul_f32_e32 v254, v240, v240
	v_pk_mul_f32 v[40:41], v[44:45], v[40:41]
	v_pk_mul_f32 v[42:43], v[46:47], v[42:43]
	v_pk_mul_f32 v[32:33], v[36:37], v[32:33]
	v_pk_mul_f32 v[34:35], v[38:39], v[34:35]
	v_pk_mul_f32 v[44:45], v[44:45], v[252:253] op_sel_hi:[1,0]
	v_pk_mul_f32 v[46:47], v[46:47], v[252:253] op_sel_hi:[1,0]
	v_pk_mul_f32 v[36:37], v[36:37], v[252:253] op_sel_hi:[1,0]
	v_pk_mul_f32 v[38:39], v[38:39], v[252:253] op_sel_hi:[1,0]
	v_exp_f32_e32 v44, v44
	v_exp_f32_e32 v45, v45
	v_exp_f32_e32 v46, v46
	v_exp_f32_e32 v47, v47
	v_exp_f32_e32 v36, v36
	v_exp_f32_e32 v37, v37
	v_exp_f32_e32 v38, v38
	v_exp_f32_e32 v39, v39
	v_pk_add_f32 v[44:45], v[44:45], 1.0 op_sel_hi:[1,0]
	v_pk_add_f32 v[46:47], v[46:47], 1.0 op_sel_hi:[1,0]
	v_pk_add_f32 v[36:37], v[36:37], 1.0 op_sel_hi:[1,0]
	v_pk_add_f32 v[38:39], v[38:39], 1.0 op_sel_hi:[1,0]
	v_rcp_f32_e32 v44, v44
	v_rcp_f32_e32 v45, v45
	v_rcp_f32_e32 v46, v46
	v_rcp_f32_e32 v47, v47
	v_rcp_f32_e32 v36, v36
	v_rcp_f32_e32 v37, v37
	v_rcp_f32_e32 v38, v38
	v_rcp_f32_e32 v39, v39
	v_pk_mul_f32 v[40:41], v[40:41], v[254:255] op_sel_hi:[1,0]
	v_pk_mul_f32 v[42:43], v[42:43], v[254:255] op_sel_hi:[1,0]
	v_pk_mul_f32 v[32:33], v[32:33], v[254:255] op_sel_hi:[1,0]
	v_pk_mul_f32 v[34:35], v[34:35], v[254:255] op_sel_hi:[1,0]
	v_pk_mul_f32 v[40:41], v[40:41], v[44:45]
	v_pk_mul_f32 v[42:43], v[42:43], v[46:47]
	v_pk_mul_f32 v[32:33], v[32:33], v[36:37]
	v_pk_mul_f32 v[34:35], v[34:35], v[38:39]
	v_cvt_pk_bf16_f32 v40, v40, v41
	v_cvt_pk_bf16_f32 v41, v42, v43
	v_cvt_pk_bf16_f32 v42, v32, v33
	v_cvt_pk_bf16_f32 v43, v34, v35
	global_store_dwordx4 v234, v[40:43], s[10:11]
	v_add_u32_e32 v235, 0x16000, v234
	v_mul_f32_e32 v252, 0xbfb8aa3b, v244
	v_mul_f32_e32 v254, v244, v244
	v_pk_mul_f32 v[24:25], v[28:29], v[24:25]
	v_pk_mul_f32 v[26:27], v[30:31], v[26:27]
	v_pk_mul_f32 v[16:17], v[20:21], v[16:17]
	v_pk_mul_f32 v[18:19], v[22:23], v[18:19]
	v_pk_mul_f32 v[28:29], v[28:29], v[252:253] op_sel_hi:[1,0]
	v_pk_mul_f32 v[30:31], v[30:31], v[252:253] op_sel_hi:[1,0]
	v_pk_mul_f32 v[20:21], v[20:21], v[252:253] op_sel_hi:[1,0]
	v_pk_mul_f32 v[22:23], v[22:23], v[252:253] op_sel_hi:[1,0]
	v_exp_f32_e32 v28, v28
	v_exp_f32_e32 v29, v29
	v_exp_f32_e32 v30, v30
	v_exp_f32_e32 v31, v31
	v_exp_f32_e32 v20, v20
	v_exp_f32_e32 v21, v21
	v_exp_f32_e32 v22, v22
	v_exp_f32_e32 v23, v23
	v_pk_add_f32 v[28:29], v[28:29], 1.0 op_sel_hi:[1,0]
	v_pk_add_f32 v[30:31], v[30:31], 1.0 op_sel_hi:[1,0]
	v_pk_add_f32 v[20:21], v[20:21], 1.0 op_sel_hi:[1,0]
	v_pk_add_f32 v[22:23], v[22:23], 1.0 op_sel_hi:[1,0]
	v_rcp_f32_e32 v28, v28
	v_rcp_f32_e32 v29, v29
	v_rcp_f32_e32 v30, v30
	v_rcp_f32_e32 v31, v31
	v_rcp_f32_e32 v20, v20
	v_rcp_f32_e32 v21, v21
	v_rcp_f32_e32 v22, v22
	v_rcp_f32_e32 v23, v23
	v_pk_mul_f32 v[24:25], v[24:25], v[254:255] op_sel_hi:[1,0]
	v_pk_mul_f32 v[26:27], v[26:27], v[254:255] op_sel_hi:[1,0]
	v_pk_mul_f32 v[16:17], v[16:17], v[254:255] op_sel_hi:[1,0]
	v_pk_mul_f32 v[18:19], v[18:19], v[254:255] op_sel_hi:[1,0]
	v_pk_mul_f32 v[24:25], v[24:25], v[28:29]
	v_pk_mul_f32 v[26:27], v[26:27], v[30:31]
	v_pk_mul_f32 v[16:17], v[16:17], v[20:21]
	v_pk_mul_f32 v[18:19], v[18:19], v[22:23]
	v_cvt_pk_bf16_f32 v24, v24, v25
	v_cvt_pk_bf16_f32 v25, v26, v27
	v_cvt_pk_bf16_f32 v26, v16, v17
	v_cvt_pk_bf16_f32 v27, v18, v19
	global_store_dwordx4 v235, v[24:27], s[10:11]
	v_add_u32_e32 v234, 0x16000, v235
	v_mul_f32_e32 v252, 0xbfb8aa3b, v248
	v_mul_f32_e32 v254, v248, v248
	v_pk_mul_f32 v[8:9], v[12:13], v[8:9]
	v_pk_mul_f32 v[10:11], v[14:15], v[10:11]
	v_pk_mul_f32 v[0:1], v[4:5], v[0:1]
	v_pk_mul_f32 v[2:3], v[6:7], v[2:3]
	v_pk_mul_f32 v[12:13], v[12:13], v[252:253] op_sel_hi:[1,0]
	v_pk_mul_f32 v[14:15], v[14:15], v[252:253] op_sel_hi:[1,0]
	v_pk_mul_f32 v[4:5], v[4:5], v[252:253] op_sel_hi:[1,0]
	v_pk_mul_f32 v[6:7], v[6:7], v[252:253] op_sel_hi:[1,0]
	v_exp_f32_e32 v12, v12
	v_exp_f32_e32 v13, v13
	v_exp_f32_e32 v14, v14
	v_exp_f32_e32 v15, v15
	v_exp_f32_e32 v4, v4
	v_exp_f32_e32 v5, v5
	v_exp_f32_e32 v6, v6
	v_exp_f32_e32 v7, v7
	v_pk_add_f32 v[12:13], v[12:13], 1.0 op_sel_hi:[1,0]
	v_pk_add_f32 v[14:15], v[14:15], 1.0 op_sel_hi:[1,0]
	v_pk_add_f32 v[4:5], v[4:5], 1.0 op_sel_hi:[1,0]
	v_pk_add_f32 v[6:7], v[6:7], 1.0 op_sel_hi:[1,0]
	v_rcp_f32_e32 v12, v12
	v_rcp_f32_e32 v13, v13
	v_rcp_f32_e32 v14, v14
	v_rcp_f32_e32 v15, v15
	v_rcp_f32_e32 v4, v4
	v_rcp_f32_e32 v5, v5
	v_rcp_f32_e32 v6, v6
	v_rcp_f32_e32 v7, v7
	v_pk_mul_f32 v[8:9], v[8:9], v[254:255] op_sel_hi:[1,0]
	v_pk_mul_f32 v[10:11], v[10:11], v[254:255] op_sel_hi:[1,0]
	v_pk_mul_f32 v[0:1], v[0:1], v[254:255] op_sel_hi:[1,0]
	v_pk_mul_f32 v[2:3], v[2:3], v[254:255] op_sel_hi:[1,0]
	v_pk_mul_f32 v[8:9], v[8:9], v[12:13]
	v_pk_mul_f32 v[10:11], v[10:11], v[14:15]
	v_pk_mul_f32 v[0:1], v[0:1], v[4:5]
	v_pk_mul_f32 v[2:3], v[2:3], v[6:7]
	v_cvt_pk_bf16_f32 v8, v8, v9
	v_cvt_pk_bf16_f32 v9, v10, v11
	v_cvt_pk_bf16_f32 v10, v0, v1
	v_cvt_pk_bf16_f32 v11, v2, v3
	global_store_dwordx4 v234, v[8:11], s[10:11]
	s_andn2_b64 vcc, exec, s[4:5]
	s_mov_b64 s[4:5], -1
	s_cbranch_vccnz .LBB0_71
	s_andn2_b64 vcc, exec, s[8:9]
	s_cbranch_vccnz .LBB0_70
	s_barrier
	s_branch .LBB0_70

.LBB0_527:
	s_cmp_eq_u32 s75, 12
	s_cselect_b64 s[48:49], -1, 0
	s_cbranch_scc0 .LBB0_526
	s_and_b64 s[50:51], s[48:49], s[22:23]
	s_andn2_b64 vcc, exec, s[50:51]
	s_cbranch_vccnz .Llast_4
	s_add_i32 m0, s57, 0x21000
	s_nop 0
	global_load_lds_dwordx4 v[144:145], off
.Llast_4:
	v_add_u32_e32 v153, s66, v147
	ds_read_b128 v[160:163], v153
	ds_read_b128 v[164:167], v153 offset:1024
	ds_read_b128 v[168:171], v153 offset:2048
	ds_read_b128 v[172:175], v153 offset:3072
	v_add_u32_e32 v153, s67, v147
	ds_read_b128 v[176:179], v153
	ds_read_b128 v[180:183], v153 offset:1024
	ds_read_b128 v[186:189], v153 offset:2048
	ds_read_b128 v[190:193], v153 offset:3072
	s_add_u32 s50, s46, 0xfffc0080
	s_addc_u32 s51, s47, -1
	s_and_b64 s[48:49], s[48:49], exec
	s_cselect_b32 s51, s29, s51
	s_cselect_b32 s50, s70, s50
	s_cselect_b32 s49, s71, s74
	s_cselect_b32 s48, s72, s73
	v_lshl_add_u64 v[154:155], s[46:47], 0, v[138:139]
	s_add_i32 m0, s57, 0xc000
	ds_read_b128 v[194:197], v150
	ds_read_b128 v[198:201], v150 offset:1024
	ds_read_b128 v[202:205], v150 offset:2048
	ds_read_b128 v[206:209], v150 offset:3072
	ds_read_b128 v[210:213], v150 offset:4096
	ds_read_b128 v[214:217], v150 offset:5120
	ds_read_b128 v[218:221], v150 offset:6144
	ds_read_b128 v[222:225], v150 offset:7168
	global_load_lds_dwordx4 v[154:155], off
	v_lshl_add_u64 v[154:155], s[46:47], 0, v[136:137]
	s_add_i32 m0, s57, 0xe000
	s_nop 0
	global_load_lds_dwordx4 v[154:155], off
	s_waitcnt vmcnt(8)
	s_waitcnt lgkmcnt(0)
	s_barrier
	s_setprio 1
	s_waitcnt lgkmcnt(0)
	v_mfma_f32_16x16x32_bf16 v[124:127], v[160:163], v[194:197], v[124:127]
	v_mfma_f32_16x16x32_bf16 v[116:119], v[168:171], v[194:197], v[116:119]
	v_mfma_f32_16x16x32_bf16 v[108:111], v[160:163], v[202:205], v[108:111]
	v_mfma_f32_16x16x32_bf16 v[100:103], v[168:171], v[202:205], v[100:103]
	v_mfma_f32_16x16x32_bf16 v[92:95], v[160:163], v[210:213], v[92:95]
	v_mfma_f32_16x16x32_bf16 v[84:87], v[168:171], v[210:213], v[84:87]
	v_mfma_f32_16x16x32_bf16 v[76:79], v[160:163], v[218:221], v[76:79]
	v_mfma_f32_16x16x32_bf16 v[68:71], v[168:171], v[218:221], v[68:71]
	v_mfma_f32_16x16x32_bf16 v[124:127], v[164:167], v[198:201], v[124:127]
	v_mfma_f32_16x16x32_bf16 v[116:119], v[172:175], v[198:201], v[116:119]
	v_mfma_f32_16x16x32_bf16 v[108:111], v[164:167], v[206:209], v[108:111]
	v_mfma_f32_16x16x32_bf16 v[100:103], v[172:175], v[206:209], v[100:103]
	v_mfma_f32_16x16x32_bf16 v[92:95], v[164:167], v[214:217], v[92:95]
	v_mfma_f32_16x16x32_bf16 v[84:87], v[172:175], v[214:217], v[84:87]
	v_mfma_f32_16x16x32_bf16 v[76:79], v[164:167], v[222:225], v[76:79]
	v_mfma_f32_16x16x32_bf16 v[68:71], v[172:175], v[222:225], v[68:71]
	s_setprio 0
	s_setprio 1
	v_mfma_f32_16x16x32_bf16 v[120:123], v[176:179], v[194:197], v[120:123]
	v_mfma_f32_16x16x32_bf16 v[112:115], v[186:189], v[194:197], v[112:115]
	v_mfma_f32_16x16x32_bf16 v[104:107], v[176:179], v[202:205], v[104:107]
	v_mfma_f32_16x16x32_bf16 v[96:99], v[186:189], v[202:205], v[96:99]
	v_mfma_f32_16x16x32_bf16 v[88:91], v[176:179], v[210:213], v[88:91]
	v_mfma_f32_16x16x32_bf16 v[80:83], v[186:189], v[210:213], v[80:83]
	v_mfma_f32_16x16x32_bf16 v[72:75], v[176:179], v[218:221], v[72:75]
	v_mfma_f32_16x16x32_bf16 v[64:67], v[186:189], v[218:221], v[64:67]
	v_mfma_f32_16x16x32_bf16 v[120:123], v[180:183], v[198:201], v[120:123]
	v_mfma_f32_16x16x32_bf16 v[112:115], v[190:193], v[198:201], v[112:115]
	v_mfma_f32_16x16x32_bf16 v[104:107], v[180:183], v[206:209], v[104:107]
	v_mfma_f32_16x16x32_bf16 v[96:99], v[190:193], v[206:209], v[96:99]
	v_mfma_f32_16x16x32_bf16 v[88:91], v[180:183], v[214:217], v[88:91]
	v_mfma_f32_16x16x32_bf16 v[80:83], v[190:193], v[214:217], v[80:83]
	v_mfma_f32_16x16x32_bf16 v[72:75], v[180:183], v[222:225], v[72:75]
	v_mfma_f32_16x16x32_bf16 v[64:67], v[190:193], v[222:225], v[64:67]
	s_setprio 0
	s_barrier
	s_add_i32 s76, s66, s54
	v_lshl_add_u64 v[154:155], s[48:49], 0, v[132:133]
	s_mov_b32 m0, s76
	ds_read_b128 v[194:197], v150 offset:16384
	ds_read_b128 v[198:201], v150 offset:17408
	ds_read_b128 v[202:205], v150 offset:18432
	ds_read_b128 v[206:209], v150 offset:19456
	ds_read_b128 v[210:213], v150 offset:20480
	ds_read_b128 v[214:217], v150 offset:21504
	ds_read_b128 v[218:221], v150 offset:22528
	ds_read_b128 v[222:225], v150 offset:23552
	global_load_lds_dwordx4 v[154:155], off
	s_add_i32 m0, s76, 0x2000
	s_add_u32 s76, s48, 0x40000
	v_lshl_add_u64 v[226:227], s[48:49], 0, v[128:129]
	s_addc_u32 s77, s49, 0
	s_add_i32 s78, s67, s54
	global_load_lds_dwordx4 v[226:227], off
	v_lshl_add_u64 v[228:229], s[76:77], 0, v[132:133]
	s_mov_b32 m0, s78
	v_lshl_add_u64 v[230:231], s[50:51], 0, v[130:131]
	global_load_lds_dwordx4 v[228:229], off
	v_lshl_add_u64 v[228:229], s[76:77], 0, v[128:129]
	s_add_i32 m0, s78, 0x2000
	s_nop 0
	global_load_lds_dwordx4 v[228:229], off
	v_lshl_add_u64 v[228:229], s[50:51], 0, v[134:135]
	s_mov_b32 m0, s57
	s_nop 0
	global_load_lds_dwordx4 v[228:229], off
	s_mov_b32 m0, s58
	s_nop 0
	global_load_lds_dwordx4 v[230:231], off
	s_waitcnt vmcnt(8)
	s_waitcnt lgkmcnt(0)
	s_barrier
	s_setprio 1
	s_waitcnt lgkmcnt(0)
	v_mfma_f32_16x16x32_bf16 v[60:63], v[160:163], v[194:197], v[60:63]
	v_mfma_f32_16x16x32_bf16 v[52:55], v[168:171], v[194:197], v[52:55]
	v_mfma_f32_16x16x32_bf16 v[44:47], v[160:163], v[202:205], v[44:47]
	v_mfma_f32_16x16x32_bf16 v[36:39], v[168:171], v[202:205], v[36:39]
	v_mfma_f32_16x16x32_bf16 v[28:31], v[160:163], v[210:213], v[28:31]
	v_mfma_f32_16x16x32_bf16 v[20:23], v[168:171], v[210:213], v[20:23]
	v_mfma_f32_16x16x32_bf16 v[12:15], v[160:163], v[218:221], v[12:15]
	v_mfma_f32_16x16x32_bf16 v[4:7], v[168:171], v[218:221], v[4:7]
	v_mfma_f32_16x16x32_bf16 v[60:63], v[164:167], v[198:201], v[60:63]
	v_mfma_f32_16x16x32_bf16 v[52:55], v[172:175], v[198:201], v[52:55]
	v_mfma_f32_16x16x32_bf16 v[44:47], v[164:167], v[206:209], v[44:47]
	v_mfma_f32_16x16x32_bf16 v[36:39], v[172:175], v[206:209], v[36:39]
	v_mfma_f32_16x16x32_bf16 v[28:31], v[164:167], v[214:217], v[28:31]
	v_mfma_f32_16x16x32_bf16 v[20:23], v[172:175], v[214:217], v[20:23]
	v_mfma_f32_16x16x32_bf16 v[12:15], v[164:167], v[222:225], v[12:15]
	v_mfma_f32_16x16x32_bf16 v[4:7], v[172:175], v[222:225], v[4:7]
	s_setprio 0
	s_setprio 1
	v_mfma_f32_16x16x32_bf16 v[56:59], v[176:179], v[194:197], v[56:59]
	v_mfma_f32_16x16x32_bf16 v[48:51], v[186:189], v[194:197], v[48:51]
	v_mfma_f32_16x16x32_bf16 v[40:43], v[176:179], v[202:205], v[40:43]
	v_mfma_f32_16x16x32_bf16 v[32:35], v[186:189], v[202:205], v[32:35]
	v_mfma_f32_16x16x32_bf16 v[24:27], v[176:179], v[210:213], v[24:27]
	v_mfma_f32_16x16x32_bf16 v[16:19], v[186:189], v[210:213], v[16:19]
	v_mfma_f32_16x16x32_bf16 v[8:11], v[176:179], v[218:221], v[8:11]
	v_mfma_f32_16x16x32_bf16 v[0:3], v[186:189], v[218:221], v[0:3]
	v_mfma_f32_16x16x32_bf16 v[56:59], v[180:183], v[198:201], v[56:59]
	v_mfma_f32_16x16x32_bf16 v[48:51], v[190:193], v[198:201], v[48:51]
	v_mfma_f32_16x16x32_bf16 v[40:43], v[180:183], v[206:209], v[40:43]
	v_mfma_f32_16x16x32_bf16 v[32:35], v[190:193], v[206:209], v[32:35]
	v_mfma_f32_16x16x32_bf16 v[24:27], v[180:183], v[214:217], v[24:27]
	v_mfma_f32_16x16x32_bf16 v[16:19], v[190:193], v[214:217], v[16:19]
	v_mfma_f32_16x16x32_bf16 v[8:11], v[180:183], v[222:225], v[8:11]
	v_mfma_f32_16x16x32_bf16 v[0:3], v[190:193], v[222:225], v[0:3]
	s_setprio 0
	s_barrier
	s_add_i32 s76, 0, 0x18000
	v_add_u32_e32 v153, s76, v147
	s_add_i32 s77, 0, 0x1c000
	ds_read_b128 v[160:163], v153
	ds_read_b128 v[164:167], v153 offset:1024
	ds_read_b128 v[168:171], v153 offset:2048
	ds_read_b128 v[172:175], v153 offset:3072
	v_add_u32_e32 v153, s77, v147
	ds_read_b128 v[176:179], v153
	ds_read_b128 v[180:183], v153 offset:1024
	ds_read_b128 v[186:189], v153 offset:2048
	ds_read_b128 v[190:193], v153 offset:3072
	s_add_u32 s50, s50, 0x40000
	s_addc_u32 s51, s51, 0
	s_mov_b32 m0, s59
	v_lshl_add_u64 v[232:233], s[50:51], 0, v[134:135]
	ds_read_b128 v[194:197], v150 offset:32768
	ds_read_b128 v[198:201], v150 offset:33792
	ds_read_b128 v[202:205], v150 offset:34816
	ds_read_b128 v[206:209], v150 offset:35840
	ds_read_b128 v[210:213], v150 offset:36864
	ds_read_b128 v[214:217], v150 offset:37888
	ds_read_b128 v[218:221], v150 offset:38912
	ds_read_b128 v[222:225], v150 offset:39936
	global_load_lds_dwordx4 v[232:233], off
	v_lshl_add_u64 v[232:233], s[50:51], 0, v[130:131]
	s_mov_b32 m0, s60
	s_nop 0
	global_load_lds_dwordx4 v[232:233], off
	s_waitcnt vmcnt(8)
	s_waitcnt lgkmcnt(0)
	s_barrier
	s_setprio 1
	s_waitcnt lgkmcnt(0)
	v_mfma_f32_16x16x32_bf16 v[124:127], v[160:163], v[194:197], v[124:127]
	v_mfma_f32_16x16x32_bf16 v[116:119], v[168:171], v[194:197], v[116:119]
	v_mfma_f32_16x16x32_bf16 v[108:111], v[160:163], v[202:205], v[108:111]
	v_mfma_f32_16x16x32_bf16 v[100:103], v[168:171], v[202:205], v[100:103]
	v_mfma_f32_16x16x32_bf16 v[92:95], v[160:163], v[210:213], v[92:95]
	v_mfma_f32_16x16x32_bf16 v[84:87], v[168:171], v[210:213], v[84:87]
	v_mfma_f32_16x16x32_bf16 v[76:79], v[160:163], v[218:221], v[76:79]
	v_mfma_f32_16x16x32_bf16 v[68:71], v[168:171], v[218:221], v[68:71]
	v_mfma_f32_16x16x32_bf16 v[124:127], v[164:167], v[198:201], v[124:127]
	v_mfma_f32_16x16x32_bf16 v[116:119], v[172:175], v[198:201], v[116:119]
	v_mfma_f32_16x16x32_bf16 v[108:111], v[164:167], v[206:209], v[108:111]
	v_mfma_f32_16x16x32_bf16 v[100:103], v[172:175], v[206:209], v[100:103]
	v_mfma_f32_16x16x32_bf16 v[92:95], v[164:167], v[214:217], v[92:95]
	v_mfma_f32_16x16x32_bf16 v[84:87], v[172:175], v[214:217], v[84:87]
	v_mfma_f32_16x16x32_bf16 v[76:79], v[164:167], v[222:225], v[76:79]
	v_mfma_f32_16x16x32_bf16 v[68:71], v[172:175], v[222:225], v[68:71]
	s_setprio 0
	s_setprio 1
	v_mfma_f32_16x16x32_bf16 v[120:123], v[176:179], v[194:197], v[120:123]
	v_mfma_f32_16x16x32_bf16 v[112:115], v[186:189], v[194:197], v[112:115]
	v_mfma_f32_16x16x32_bf16 v[104:107], v[176:179], v[202:205], v[104:107]
	v_mfma_f32_16x16x32_bf16 v[96:99], v[186:189], v[202:205], v[96:99]
	v_mfma_f32_16x16x32_bf16 v[88:91], v[176:179], v[210:213], v[88:91]
	v_mfma_f32_16x16x32_bf16 v[80:83], v[186:189], v[210:213], v[80:83]
	v_mfma_f32_16x16x32_bf16 v[72:75], v[176:179], v[218:221], v[72:75]
	v_mfma_f32_16x16x32_bf16 v[64:67], v[186:189], v[218:221], v[64:67]
	v_mfma_f32_16x16x32_bf16 v[120:123], v[180:183], v[198:201], v[120:123]
	v_mfma_f32_16x16x32_bf16 v[112:115], v[190:193], v[198:201], v[112:115]
	v_mfma_f32_16x16x32_bf16 v[104:107], v[180:183], v[206:209], v[104:107]
	v_mfma_f32_16x16x32_bf16 v[96:99], v[190:193], v[206:209], v[96:99]
	v_mfma_f32_16x16x32_bf16 v[88:91], v[180:183], v[214:217], v[88:91]
	v_mfma_f32_16x16x32_bf16 v[80:83], v[190:193], v[214:217], v[80:83]
	v_mfma_f32_16x16x32_bf16 v[72:75], v[180:183], v[222:225], v[72:75]
	v_mfma_f32_16x16x32_bf16 v[64:67], v[190:193], v[222:225], v[64:67]
	s_setprio 0
	s_barrier
	v_add_u32_e32 v234, 0x21000, v151
	ds_read_b128 v[236:239], v234
	ds_read_b128 v[240:243], v234 offset:256
	ds_read_b128 v[244:247], v234 offset:512
	ds_read_b128 v[248:251], v234 offset:768
	v_add_u32_e32 v235, s27, v146
	v_mul_u32_u24_e32 v235, 0x1600, v235
	v_lshl_or_b32 v234, s69, 7, v149
	v_lshl_add_u32 v235, v234, 1, v235
	s_add_i32 s50, s76, s54
	v_lshl_add_u64 v[154:155], v[154:155], 0, s[20:21]
	s_mov_b32 m0, s50
	ds_read_b128 v[194:197], v150 offset:49152
	ds_read_b128 v[198:201], v150 offset:50176
	ds_read_b128 v[202:205], v150 offset:51200
	ds_read_b128 v[206:209], v150 offset:52224
	ds_read_b128 v[210:213], v150 offset:53248
	ds_read_b128 v[214:217], v150 offset:54272
	ds_read_b128 v[218:221], v150 offset:55296
	ds_read_b128 v[222:225], v150 offset:56320
	global_load_lds_dwordx4 v[154:155], off
	s_add_i32 m0, s50, 0x2000
	s_add_u32 s48, s48, 0x40080
	v_lshl_add_u64 v[154:155], v[226:227], 0, s[20:21]
	s_addc_u32 s49, s49, 0
	s_add_i32 s50, s77, s54
	global_load_lds_dwordx4 v[154:155], off
	v_lshl_add_u64 v[154:155], s[48:49], 0, v[132:133]
	s_mov_b32 m0, s50
	s_nop 0
	global_load_lds_dwordx4 v[154:155], off
	v_lshl_add_u64 v[154:155], s[48:49], 0, v[128:129]
	s_add_i32 m0, s50, 0x2000
	s_nop 0
	global_load_lds_dwordx4 v[154:155], off
	v_lshl_add_u64 v[154:155], v[228:229], 0, s[20:21]
	s_mov_b32 m0, s62
	s_nop 0
	global_load_lds_dwordx4 v[154:155], off
	v_lshl_add_u64 v[154:155], v[230:231], 0, s[20:21]
	s_mov_b32 m0, s63
	s_nop 0
	global_load_lds_dwordx4 v[154:155], off
	s_waitcnt lgkmcnt(8)
	v_add_f32_e32 v236, v236, v237
	v_add_f32_e32 v238, v238, v239
	v_add_f32_e32 v240, v240, v241
	v_add_f32_e32 v242, v242, v243
	v_add_f32_e32 v244, v244, v245
	v_add_f32_e32 v246, v246, v247
	v_add_f32_e32 v248, v248, v249
	v_add_f32_e32 v250, v250, v251
	v_add_f32_e32 v236, v236, v238
	v_add_f32_e32 v240, v240, v242
	v_add_f32_e32 v244, v244, v246
	v_add_f32_e32 v248, v248, v250
	v_fmamk_f32 v236, v236, 0x3a800000, v152
	v_fmamk_f32 v240, v240, 0x3a800000, v152
	v_fmamk_f32 v244, v244, 0x3a800000, v152
	v_fmamk_f32 v248, v248, 0x3a800000, v152
	v_rsq_f32_e32 v236, v236
	v_rsq_f32_e32 v240, v240
	v_rsq_f32_e32 v244, v244
	v_rsq_f32_e32 v248, v248
	v_mul_f32_e32 v252, 0xbfb8aa3b, v236
	v_mul_f32_e32 v254, v236, v236
	v_pk_mul_f32 v[120:121], v[124:125], v[120:121]
	v_pk_mul_f32 v[122:123], v[126:127], v[122:123]
	v_pk_mul_f32 v[112:113], v[116:117], v[112:113]
	v_pk_mul_f32 v[114:115], v[118:119], v[114:115]
	v_pk_mul_f32 v[124:125], v[124:125], v[252:253] op_sel_hi:[1,0]
	v_pk_mul_f32 v[126:127], v[126:127], v[252:253] op_sel_hi:[1,0]
	v_pk_mul_f32 v[116:117], v[116:117], v[252:253] op_sel_hi:[1,0]
	v_pk_mul_f32 v[118:119], v[118:119], v[252:253] op_sel_hi:[1,0]
	v_exp_f32_e32 v124, v124
	v_exp_f32_e32 v125, v125
	v_exp_f32_e32 v126, v126
	v_exp_f32_e32 v127, v127
	v_exp_f32_e32 v116, v116
	v_exp_f32_e32 v117, v117
	v_exp_f32_e32 v118, v118
	v_exp_f32_e32 v119, v119
	v_pk_add_f32 v[124:125], v[124:125], 1.0 op_sel_hi:[1,0]
	v_pk_add_f32 v[126:127], v[126:127], 1.0 op_sel_hi:[1,0]
	v_pk_add_f32 v[116:117], v[116:117], 1.0 op_sel_hi:[1,0]
	v_pk_add_f32 v[118:119], v[118:119], 1.0 op_sel_hi:[1,0]
	v_rcp_f32_e32 v124, v124
	v_rcp_f32_e32 v125, v125
	v_rcp_f32_e32 v126, v126
	v_rcp_f32_e32 v127, v127
	v_rcp_f32_e32 v116, v116
	v_rcp_f32_e32 v117, v117
	v_rcp_f32_e32 v118, v118
	v_rcp_f32_e32 v119, v119
	v_pk_mul_f32 v[120:121], v[120:121], v[254:255] op_sel_hi:[1,0]
	v_pk_mul_f32 v[122:123], v[122:123], v[254:255] op_sel_hi:[1,0]
	v_pk_mul_f32 v[112:113], v[112:113], v[254:255] op_sel_hi:[1,0]
	v_pk_mul_f32 v[114:115], v[114:115], v[254:255] op_sel_hi:[1,0]
	v_pk_mul_f32 v[120:121], v[120:121], v[124:125]
	v_pk_mul_f32 v[122:123], v[122:123], v[126:127]
	v_pk_mul_f32 v[112:113], v[112:113], v[116:117]
	v_pk_mul_f32 v[114:115], v[114:115], v[118:119]
	v_cvt_pk_bf16_f32 v120, v120, v121
	v_cvt_pk_bf16_f32 v121, v122, v123
	v_cvt_pk_bf16_f32 v122, v112, v113
	v_cvt_pk_bf16_f32 v123, v114, v115
	global_store_dwordx4 v235, v[120:123], s[14:15]
	v_add_u32_e32 v234, 0x16000, v235
	v_mul_f32_e32 v252, 0xbfb8aa3b, v240
	v_mul_f32_e32 v254, v240, v240
	v_pk_mul_f32 v[104:105], v[108:109], v[104:105]
	v_pk_mul_f32 v[106:107], v[110:111], v[106:107]
	v_pk_mul_f32 v[96:97], v[100:101], v[96:97]
	v_pk_mul_f32 v[98:99], v[102:103], v[98:99]
	v_pk_mul_f32 v[108:109], v[108:109], v[252:253] op_sel_hi:[1,0]
	v_pk_mul_f32 v[110:111], v[110:111], v[252:253] op_sel_hi:[1,0]
	v_pk_mul_f32 v[100:101], v[100:101], v[252:253] op_sel_hi:[1,0]
	v_pk_mul_f32 v[102:103], v[102:103], v[252:253] op_sel_hi:[1,0]
	v_exp_f32_e32 v108, v108
	v_exp_f32_e32 v109, v109
	v_exp_f32_e32 v110, v110
	v_exp_f32_e32 v111, v111
	v_exp_f32_e32 v100, v100
	v_exp_f32_e32 v101, v101
	v_exp_f32_e32 v102, v102
	v_exp_f32_e32 v103, v103
	v_pk_add_f32 v[108:109], v[108:109], 1.0 op_sel_hi:[1,0]
	v_pk_add_f32 v[110:111], v[110:111], 1.0 op_sel_hi:[1,0]
	v_pk_add_f32 v[100:101], v[100:101], 1.0 op_sel_hi:[1,0]
	v_pk_add_f32 v[102:103], v[102:103], 1.0 op_sel_hi:[1,0]
	v_rcp_f32_e32 v108, v108
	v_rcp_f32_e32 v109, v109
	v_rcp_f32_e32 v110, v110
	v_rcp_f32_e32 v111, v111
	v_rcp_f32_e32 v100, v100
	v_rcp_f32_e32 v101, v101
	v_rcp_f32_e32 v102, v102
	v_rcp_f32_e32 v103, v103
	v_pk_mul_f32 v[104:105], v[104:105], v[254:255] op_sel_hi:[1,0]
	v_pk_mul_f32 v[106:107], v[106:107], v[254:255] op_sel_hi:[1,0]
	v_pk_mul_f32 v[96:97], v[96:97], v[254:255] op_sel_hi:[1,0]
	v_pk_mul_f32 v[98:99], v[98:99], v[254:255] op_sel_hi:[1,0]
	v_pk_mul_f32 v[104:105], v[104:105], v[108:109]
	v_pk_mul_f32 v[106:107], v[106:107], v[110:111]
	v_pk_mul_f32 v[96:97], v[96:97], v[100:101]
	v_pk_mul_f32 v[98:99], v[98:99], v[102:103]
	v_cvt_pk_bf16_f32 v104, v104, v105
	v_cvt_pk_bf16_f32 v105, v106, v107
	v_cvt_pk_bf16_f32 v106, v96, v97
	v_cvt_pk_bf16_f32 v107, v98, v99
	global_store_dwordx4 v234, v[104:107], s[14:15]
	v_add_u32_e32 v235, 0x16000, v234
	v_mul_f32_e32 v252, 0xbfb8aa3b, v244
	v_mul_f32_e32 v254, v244, v244
	v_pk_mul_f32 v[88:89], v[92:93], v[88:89]
	v_pk_mul_f32 v[90:91], v[94:95], v[90:91]
	v_pk_mul_f32 v[80:81], v[84:85], v[80:81]
	v_pk_mul_f32 v[82:83], v[86:87], v[82:83]
	v_pk_mul_f32 v[92:93], v[92:93], v[252:253] op_sel_hi:[1,0]
	v_pk_mul_f32 v[94:95], v[94:95], v[252:253] op_sel_hi:[1,0]
	v_pk_mul_f32 v[84:85], v[84:85], v[252:253] op_sel_hi:[1,0]
	v_pk_mul_f32 v[86:87], v[86:87], v[252:253] op_sel_hi:[1,0]
	v_exp_f32_e32 v92, v92
	v_exp_f32_e32 v93, v93
	v_exp_f32_e32 v94, v94
	v_exp_f32_e32 v95, v95
	v_exp_f32_e32 v84, v84
	v_exp_f32_e32 v85, v85
	v_exp_f32_e32 v86, v86
	v_exp_f32_e32 v87, v87
	v_pk_add_f32 v[92:93], v[92:93], 1.0 op_sel_hi:[1,0]
	v_pk_add_f32 v[94:95], v[94:95], 1.0 op_sel_hi:[1,0]
	v_pk_add_f32 v[84:85], v[84:85], 1.0 op_sel_hi:[1,0]
	v_pk_add_f32 v[86:87], v[86:87], 1.0 op_sel_hi:[1,0]
	v_rcp_f32_e32 v92, v92
	v_rcp_f32_e32 v93, v93
	v_rcp_f32_e32 v94, v94
	v_rcp_f32_e32 v95, v95
	v_rcp_f32_e32 v84, v84
	v_rcp_f32_e32 v85, v85
	v_rcp_f32_e32 v86, v86
	v_rcp_f32_e32 v87, v87
	v_pk_mul_f32 v[88:89], v[88:89], v[254:255] op_sel_hi:[1,0]
	v_pk_mul_f32 v[90:91], v[90:91], v[254:255] op_sel_hi:[1,0]
	v_pk_mul_f32 v[80:81], v[80:81], v[254:255] op_sel_hi:[1,0]
	v_pk_mul_f32 v[82:83], v[82:83], v[254:255] op_sel_hi:[1,0]
	v_pk_mul_f32 v[88:89], v[88:89], v[92:93]
	v_pk_mul_f32 v[90:91], v[90:91], v[94:95]
	v_pk_mul_f32 v[80:81], v[80:81], v[84:85]
	v_pk_mul_f32 v[82:83], v[82:83], v[86:87]
	v_cvt_pk_bf16_f32 v88, v88, v89
	v_cvt_pk_bf16_f32 v89, v90, v91
	v_cvt_pk_bf16_f32 v90, v80, v81
	v_cvt_pk_bf16_f32 v91, v82, v83
	global_store_dwordx4 v235, v[88:91], s[14:15]
	v_add_u32_e32 v234, 0x16000, v235
	v_mul_f32_e32 v252, 0xbfb8aa3b, v248
	v_mul_f32_e32 v254, v248, v248
	v_pk_mul_f32 v[72:73], v[76:77], v[72:73]
	v_pk_mul_f32 v[74:75], v[78:79], v[74:75]
	v_pk_mul_f32 v[64:65], v[68:69], v[64:65]
	v_pk_mul_f32 v[66:67], v[70:71], v[66:67]
	v_pk_mul_f32 v[76:77], v[76:77], v[252:253] op_sel_hi:[1,0]
	v_pk_mul_f32 v[78:79], v[78:79], v[252:253] op_sel_hi:[1,0]
	v_pk_mul_f32 v[68:69], v[68:69], v[252:253] op_sel_hi:[1,0]
	v_pk_mul_f32 v[70:71], v[70:71], v[252:253] op_sel_hi:[1,0]
	v_exp_f32_e32 v76, v76
	v_exp_f32_e32 v77, v77
	v_exp_f32_e32 v78, v78
	v_exp_f32_e32 v79, v79
	v_exp_f32_e32 v68, v68
	v_exp_f32_e32 v69, v69
	v_exp_f32_e32 v70, v70
	v_exp_f32_e32 v71, v71
	v_pk_add_f32 v[76:77], v[76:77], 1.0 op_sel_hi:[1,0]
	v_pk_add_f32 v[78:79], v[78:79], 1.0 op_sel_hi:[1,0]
	v_pk_add_f32 v[68:69], v[68:69], 1.0 op_sel_hi:[1,0]
	v_pk_add_f32 v[70:71], v[70:71], 1.0 op_sel_hi:[1,0]
	v_rcp_f32_e32 v76, v76
	v_rcp_f32_e32 v77, v77
	v_rcp_f32_e32 v78, v78
	v_rcp_f32_e32 v79, v79
	v_rcp_f32_e32 v68, v68
	v_rcp_f32_e32 v69, v69
	v_rcp_f32_e32 v70, v70
	v_rcp_f32_e32 v71, v71
	v_pk_mul_f32 v[72:73], v[72:73], v[254:255] op_sel_hi:[1,0]
	v_pk_mul_f32 v[74:75], v[74:75], v[254:255] op_sel_hi:[1,0]
	v_pk_mul_f32 v[64:65], v[64:65], v[254:255] op_sel_hi:[1,0]
	v_pk_mul_f32 v[66:67], v[66:67], v[254:255] op_sel_hi:[1,0]
	v_pk_mul_f32 v[72:73], v[72:73], v[76:77]
	v_pk_mul_f32 v[74:75], v[74:75], v[78:79]
	v_pk_mul_f32 v[64:65], v[64:65], v[68:69]
	v_pk_mul_f32 v[66:67], v[66:67], v[70:71]
	v_cvt_pk_bf16_f32 v72, v72, v73
	v_cvt_pk_bf16_f32 v73, v74, v75
	v_cvt_pk_bf16_f32 v74, v64, v65
	v_cvt_pk_bf16_f32 v75, v66, v67
	global_store_dwordx4 v234, v[72:75], s[14:15]
	s_waitcnt vmcnt(12)
	s_waitcnt lgkmcnt(0)
	s_barrier
	s_setprio 1
	s_waitcnt lgkmcnt(0)
	v_mfma_f32_16x16x32_bf16 v[60:63], v[160:163], v[194:197], v[60:63]
	v_mfma_f32_16x16x32_bf16 v[52:55], v[168:171], v[194:197], v[52:55]
	v_mfma_f32_16x16x32_bf16 v[44:47], v[160:163], v[202:205], v[44:47]
	v_mfma_f32_16x16x32_bf16 v[36:39], v[168:171], v[202:205], v[36:39]
	v_mfma_f32_16x16x32_bf16 v[28:31], v[160:163], v[210:213], v[28:31]
	v_mfma_f32_16x16x32_bf16 v[20:23], v[168:171], v[210:213], v[20:23]
	v_mfma_f32_16x16x32_bf16 v[12:15], v[160:163], v[218:221], v[12:15]
	v_mfma_f32_16x16x32_bf16 v[4:7], v[168:171], v[218:221], v[4:7]
	v_mfma_f32_16x16x32_bf16 v[60:63], v[164:167], v[198:201], v[60:63]
	v_mfma_f32_16x16x32_bf16 v[52:55], v[172:175], v[198:201], v[52:55]
	v_mfma_f32_16x16x32_bf16 v[44:47], v[164:167], v[206:209], v[44:47]
	v_mfma_f32_16x16x32_bf16 v[36:39], v[172:175], v[206:209], v[36:39]
	v_mfma_f32_16x16x32_bf16 v[28:31], v[164:167], v[214:217], v[28:31]
	v_mfma_f32_16x16x32_bf16 v[20:23], v[172:175], v[214:217], v[20:23]
	v_mfma_f32_16x16x32_bf16 v[12:15], v[164:167], v[222:225], v[12:15]
	v_mfma_f32_16x16x32_bf16 v[4:7], v[172:175], v[222:225], v[4:7]
	s_setprio 0
	s_setprio 1
	v_mfma_f32_16x16x32_bf16 v[56:59], v[176:179], v[194:197], v[56:59]
	v_mfma_f32_16x16x32_bf16 v[48:51], v[186:189], v[194:197], v[48:51]
	v_mfma_f32_16x16x32_bf16 v[40:43], v[176:179], v[202:205], v[40:43]
	v_mfma_f32_16x16x32_bf16 v[32:35], v[186:189], v[202:205], v[32:35]
	v_mfma_f32_16x16x32_bf16 v[24:27], v[176:179], v[210:213], v[24:27]
	v_mfma_f32_16x16x32_bf16 v[16:19], v[186:189], v[210:213], v[16:19]
	v_mfma_f32_16x16x32_bf16 v[8:11], v[176:179], v[218:221], v[8:11]
	v_mfma_f32_16x16x32_bf16 v[0:3], v[186:189], v[218:221], v[0:3]
	v_mfma_f32_16x16x32_bf16 v[56:59], v[180:183], v[198:201], v[56:59]
	v_mfma_f32_16x16x32_bf16 v[48:51], v[190:193], v[198:201], v[48:51]
	v_mfma_f32_16x16x32_bf16 v[40:43], v[180:183], v[206:209], v[40:43]
	v_mfma_f32_16x16x32_bf16 v[32:35], v[190:193], v[206:209], v[32:35]
	v_mfma_f32_16x16x32_bf16 v[24:27], v[180:183], v[214:217], v[24:27]
	v_mfma_f32_16x16x32_bf16 v[16:19], v[190:193], v[214:217], v[16:19]
	v_mfma_f32_16x16x32_bf16 v[8:11], v[180:183], v[222:225], v[8:11]
	v_mfma_f32_16x16x32_bf16 v[0:3], v[190:193], v[222:225], v[0:3]
	s_setprio 0
	s_barrier
	s_add_i32 s75, s75, 2
	s_add_u32 s73, s73, 0x100
	s_addc_u32 s74, s74, 0
	s_add_u32 s46, s46, 0x100
	s_addc_u32 s47, s47, 0

.LBB0_531:
	v_add_u32_e32 v235, 0x84000, v235
	v_add_u32_e32 v234, 0x21800, v151
	ds_read_b128 v[236:239], v234
	ds_read_b128 v[240:243], v234 offset:256
	ds_read_b128 v[244:247], v234 offset:512
	ds_read_b128 v[248:251], v234 offset:768
	s_waitcnt lgkmcnt(0)
	v_add_f32_e32 v236, v236, v237
	v_add_f32_e32 v238, v238, v239
	v_add_f32_e32 v240, v240, v241
	v_add_f32_e32 v242, v242, v243
	v_add_f32_e32 v244, v244, v245
	v_add_f32_e32 v246, v246, v247
	v_add_f32_e32 v248, v248, v249
	v_add_f32_e32 v250, v250, v251
	v_add_f32_e32 v236, v236, v238
	v_add_f32_e32 v240, v240, v242
	v_add_f32_e32 v244, v244, v246
	v_add_f32_e32 v248, v248, v250
	v_fmamk_f32 v236, v236, 0x3a800000, v152
	v_fmamk_f32 v240, v240, 0x3a800000, v152
	v_fmamk_f32 v244, v244, 0x3a800000, v152
	v_fmamk_f32 v248, v248, 0x3a800000, v152
	v_rsq_f32_e32 v236, v236
	v_rsq_f32_e32 v240, v240
	v_rsq_f32_e32 v244, v244
	v_rsq_f32_e32 v248, v248
	v_mul_f32_e32 v252, 0xbfb8aa3b, v236
	v_mul_f32_e32 v254, v236, v236
	v_pk_mul_f32 v[56:57], v[60:61], v[56:57]
	v_pk_mul_f32 v[58:59], v[62:63], v[58:59]
	v_pk_mul_f32 v[48:49], v[52:53], v[48:49]
	v_pk_mul_f32 v[50:51], v[54:55], v[50:51]
	v_pk_mul_f32 v[60:61], v[60:61], v[252:253] op_sel_hi:[1,0]
	v_pk_mul_f32 v[62:63], v[62:63], v[252:253] op_sel_hi:[1,0]
	v_pk_mul_f32 v[52:53], v[52:53], v[252:253] op_sel_hi:[1,0]
	v_pk_mul_f32 v[54:55], v[54:55], v[252:253] op_sel_hi:[1,0]
	v_exp_f32_e32 v60, v60
	v_exp_f32_e32 v61, v61
	v_exp_f32_e32 v62, v62
	v_exp_f32_e32 v63, v63
	v_exp_f32_e32 v52, v52
	v_exp_f32_e32 v53, v53
	v_exp_f32_e32 v54, v54
	v_exp_f32_e32 v55, v55
	v_pk_add_f32 v[60:61], v[60:61], 1.0 op_sel_hi:[1,0]
	v_pk_add_f32 v[62:63], v[62:63], 1.0 op_sel_hi:[1,0]
	v_pk_add_f32 v[52:53], v[52:53], 1.0 op_sel_hi:[1,0]
	v_pk_add_f32 v[54:55], v[54:55], 1.0 op_sel_hi:[1,0]
	v_rcp_f32_e32 v60, v60
	v_rcp_f32_e32 v61, v61
	v_rcp_f32_e32 v62, v62
	v_rcp_f32_e32 v63, v63
	v_rcp_f32_e32 v52, v52
	v_rcp_f32_e32 v53, v53
	v_rcp_f32_e32 v54, v54
	v_rcp_f32_e32 v55, v55
	v_pk_mul_f32 v[56:57], v[56:57], v[254:255] op_sel_hi:[1,0]
	v_pk_mul_f32 v[58:59], v[58:59], v[254:255] op_sel_hi:[1,0]
	v_pk_mul_f32 v[48:49], v[48:49], v[254:255] op_sel_hi:[1,0]
	v_pk_mul_f32 v[50:51], v[50:51], v[254:255] op_sel_hi:[1,0]
	v_pk_mul_f32 v[56:57], v[56:57], v[60:61]
	v_pk_mul_f32 v[58:59], v[58:59], v[62:63]
	v_pk_mul_f32 v[48:49], v[48:49], v[52:53]
	v_pk_mul_f32 v[50:51], v[50:51], v[54:55]
	v_cvt_pk_bf16_f32 v56, v56, v57
	v_cvt_pk_bf16_f32 v57, v58, v59
	v_cvt_pk_bf16_f32 v58, v48, v49
	v_cvt_pk_bf16_f32 v59, v50, v51
	global_store_dwordx4 v235, v[56:59], s[14:15]
	v_add_u32_e32 v234, 0x16000, v235
	v_mul_f32_e32 v252, 0xbfb8aa3b, v240
	v_mul_f32_e32 v254, v240, v240
	v_pk_mul_f32 v[40:41], v[44:45], v[40:41]
	v_pk_mul_f32 v[42:43], v[46:47], v[42:43]
	v_pk_mul_f32 v[32:33], v[36:37], v[32:33]
	v_pk_mul_f32 v[34:35], v[38:39], v[34:35]
	v_pk_mul_f32 v[44:45], v[44:45], v[252:253] op_sel_hi:[1,0]
	v_pk_mul_f32 v[46:47], v[46:47], v[252:253] op_sel_hi:[1,0]
	v_pk_mul_f32 v[36:37], v[36:37], v[252:253] op_sel_hi:[1,0]
	v_pk_mul_f32 v[38:39], v[38:39], v[252:253] op_sel_hi:[1,0]
	v_exp_f32_e32 v44, v44
	v_exp_f32_e32 v45, v45
	v_exp_f32_e32 v46, v46
	v_exp_f32_e32 v47, v47
	v_exp_f32_e32 v36, v36
	v_exp_f32_e32 v37, v37
	v_exp_f32_e32 v38, v38
	v_exp_f32_e32 v39, v39
	v_pk_add_f32 v[44:45], v[44:45], 1.0 op_sel_hi:[1,0]
	v_pk_add_f32 v[46:47], v[46:47], 1.0 op_sel_hi:[1,0]
	v_pk_add_f32 v[36:37], v[36:37], 1.0 op_sel_hi:[1,0]
	v_pk_add_f32 v[38:39], v[38:39], 1.0 op_sel_hi:[1,0]
	v_rcp_f32_e32 v44, v44
	v_rcp_f32_e32 v45, v45
	v_rcp_f32_e32 v46, v46
	v_rcp_f32_e32 v47, v47
	v_rcp_f32_e32 v36, v36
	v_rcp_f32_e32 v37, v37
	v_rcp_f32_e32 v38, v38
	v_rcp_f32_e32 v39, v39
	v_pk_mul_f32 v[40:41], v[40:41], v[254:255] op_sel_hi:[1,0]
	v_pk_mul_f32 v[42:43], v[42:43], v[254:255] op_sel_hi:[1,0]
	v_pk_mul_f32 v[32:33], v[32:33], v[254:255] op_sel_hi:[1,0]
	v_pk_mul_f32 v[34:35], v[34:35], v[254:255] op_sel_hi:[1,0]
	v_pk_mul_f32 v[40:41], v[40:41], v[44:45]
	v_pk_mul_f32 v[42:43], v[42:43], v[46:47]
	v_pk_mul_f32 v[32:33], v[32:33], v[36:37]
	v_pk_mul_f32 v[34:35], v[34:35], v[38:39]
	v_cvt_pk_bf16_f32 v40, v40, v41
	v_cvt_pk_bf16_f32 v41, v42, v43
	v_cvt_pk_bf16_f32 v42, v32, v33
	v_cvt_pk_bf16_f32 v43, v34, v35
	global_store_dwordx4 v234, v[40:43], s[14:15]
	v_add_u32_e32 v235, 0x16000, v234
	v_mul_f32_e32 v252, 0xbfb8aa3b, v244
	v_mul_f32_e32 v254, v244, v244
	v_pk_mul_f32 v[24:25], v[28:29], v[24:25]
	v_pk_mul_f32 v[26:27], v[30:31], v[26:27]
	v_pk_mul_f32 v[16:17], v[20:21], v[16:17]
	v_pk_mul_f32 v[18:19], v[22:23], v[18:19]
	v_pk_mul_f32 v[28:29], v[28:29], v[252:253] op_sel_hi:[1,0]
	v_pk_mul_f32 v[30:31], v[30:31], v[252:253] op_sel_hi:[1,0]
	v_pk_mul_f32 v[20:21], v[20:21], v[252:253] op_sel_hi:[1,0]
	v_pk_mul_f32 v[22:23], v[22:23], v[252:253] op_sel_hi:[1,0]
	v_exp_f32_e32 v28, v28
	v_exp_f32_e32 v29, v29
	v_exp_f32_e32 v30, v30
	v_exp_f32_e32 v31, v31
	v_exp_f32_e32 v20, v20
	v_exp_f32_e32 v21, v21
	v_exp_f32_e32 v22, v22
	v_exp_f32_e32 v23, v23
	v_pk_add_f32 v[28:29], v[28:29], 1.0 op_sel_hi:[1,0]
	v_pk_add_f32 v[30:31], v[30:31], 1.0 op_sel_hi:[1,0]
	v_pk_add_f32 v[20:21], v[20:21], 1.0 op_sel_hi:[1,0]
	v_pk_add_f32 v[22:23], v[22:23], 1.0 op_sel_hi:[1,0]
	v_rcp_f32_e32 v28, v28
	v_rcp_f32_e32 v29, v29
	v_rcp_f32_e32 v30, v30
	v_rcp_f32_e32 v31, v31
	v_rcp_f32_e32 v20, v20
	v_rcp_f32_e32 v21, v21
	v_rcp_f32_e32 v22, v22
	v_rcp_f32_e32 v23, v23
	v_pk_mul_f32 v[24:25], v[24:25], v[254:255] op_sel_hi:[1,0]
	v_pk_mul_f32 v[26:27], v[26:27], v[254:255] op_sel_hi:[1,0]
	v_pk_mul_f32 v[16:17], v[16:17], v[254:255] op_sel_hi:[1,0]
	v_pk_mul_f32 v[18:19], v[18:19], v[254:255] op_sel_hi:[1,0]
	v_pk_mul_f32 v[24:25], v[24:25], v[28:29]
	v_pk_mul_f32 v[26:27], v[26:27], v[30:31]
	v_pk_mul_f32 v[16:17], v[16:17], v[20:21]
	v_pk_mul_f32 v[18:19], v[18:19], v[22:23]
	v_cvt_pk_bf16_f32 v24, v24, v25
	v_cvt_pk_bf16_f32 v25, v26, v27
	v_cvt_pk_bf16_f32 v26, v16, v17
	v_cvt_pk_bf16_f32 v27, v18, v19
	global_store_dwordx4 v235, v[24:27], s[14:15]
	v_add_u32_e32 v234, 0x16000, v235
	v_mul_f32_e32 v252, 0xbfb8aa3b, v248
	v_mul_f32_e32 v254, v248, v248
	v_pk_mul_f32 v[8:9], v[12:13], v[8:9]
	v_pk_mul_f32 v[10:11], v[14:15], v[10:11]
	v_pk_mul_f32 v[0:1], v[4:5], v[0:1]
	v_pk_mul_f32 v[2:3], v[6:7], v[2:3]
	v_pk_mul_f32 v[12:13], v[12:13], v[252:253] op_sel_hi:[1,0]
	v_pk_mul_f32 v[14:15], v[14:15], v[252:253] op_sel_hi:[1,0]
	v_pk_mul_f32 v[4:5], v[4:5], v[252:253] op_sel_hi:[1,0]
	v_pk_mul_f32 v[6:7], v[6:7], v[252:253] op_sel_hi:[1,0]
	v_exp_f32_e32 v12, v12
	v_exp_f32_e32 v13, v13
	v_exp_f32_e32 v14, v14
	v_exp_f32_e32 v15, v15
	v_exp_f32_e32 v4, v4
	v_exp_f32_e32 v5, v5
	v_exp_f32_e32 v6, v6
	v_exp_f32_e32 v7, v7
	v_pk_add_f32 v[12:13], v[12:13], 1.0 op_sel_hi:[1,0]
	v_pk_add_f32 v[14:15], v[14:15], 1.0 op_sel_hi:[1,0]
	v_pk_add_f32 v[4:5], v[4:5], 1.0 op_sel_hi:[1,0]
	v_pk_add_f32 v[6:7], v[6:7], 1.0 op_sel_hi:[1,0]
	v_rcp_f32_e32 v12, v12
	v_rcp_f32_e32 v13, v13
	v_rcp_f32_e32 v14, v14
	v_rcp_f32_e32 v15, v15
	v_rcp_f32_e32 v4, v4
	v_rcp_f32_e32 v5, v5
	v_rcp_f32_e32 v6, v6
	v_rcp_f32_e32 v7, v7
	v_pk_mul_f32 v[8:9], v[8:9], v[254:255] op_sel_hi:[1,0]
	v_pk_mul_f32 v[10:11], v[10:11], v[254:255] op_sel_hi:[1,0]
	v_pk_mul_f32 v[0:1], v[0:1], v[254:255] op_sel_hi:[1,0]
	v_pk_mul_f32 v[2:3], v[2:3], v[254:255] op_sel_hi:[1,0]
	v_pk_mul_f32 v[8:9], v[8:9], v[12:13]
	v_pk_mul_f32 v[10:11], v[10:11], v[14:15]
	v_pk_mul_f32 v[0:1], v[0:1], v[4:5]
	v_pk_mul_f32 v[2:3], v[2:3], v[6:7]
	v_cvt_pk_bf16_f32 v8, v8, v9
	v_cvt_pk_bf16_f32 v9, v10, v11
	v_cvt_pk_bf16_f32 v10, v0, v1
	v_cvt_pk_bf16_f32 v11, v2, v3
	global_store_dwordx4 v234, v[8:11], s[14:15]
	s_andn2_b64 vcc, exec, s[10:11]
	s_mov_b64 s[10:11], -1
	s_cbranch_vccnz .LBB0_522
	s_andn2_b64 vcc, exec, s[12:13]
	s_cbranch_vccnz .LBB0_521
	s_barrier
	s_branch .LBB0_521

.LBB0_1098:
	s_cmp_eq_u32 s70, 12
	s_cselect_b64 s[44:45], -1, 0
	s_cbranch_scc0 .LBB0_1097
	s_and_b64 s[46:47], s[44:45], s[16:17]
	s_andn2_b64 vcc, exec, s[46:47]
	s_cbranch_vccnz .Llast_10
	s_add_i32 m0, s52, 0x21000
	s_nop 0
	global_load_lds_dwordx4 v[144:145], off
.Llast_10:
	v_add_u32_e32 v153, s61, v147
	ds_read_b128 v[160:163], v153
	ds_read_b128 v[164:167], v153 offset:1024
	ds_read_b128 v[168:171], v153 offset:2048
	ds_read_b128 v[172:175], v153 offset:3072
	v_add_u32_e32 v153, s62, v147
	ds_read_b128 v[176:179], v153
	ds_read_b128 v[180:183], v153 offset:1024
	ds_read_b128 v[184:187], v153 offset:2048
	ds_read_b128 v[188:191], v153 offset:3072
	s_add_u32 s46, s30, 0xfffc0080
	s_addc_u32 s47, s31, -1
	s_and_b64 s[44:45], s[44:45], exec
	s_cselect_b32 s47, s25, s47
	s_cselect_b32 s46, s65, s46
	s_cselect_b32 s45, s66, s69
	s_cselect_b32 s44, s67, s68
	v_lshl_add_u64 v[154:155], s[30:31], 0, v[138:139]
	s_add_i32 m0, s52, 0xc000
	ds_read_b128 v[192:195], v150
	ds_read_b128 v[196:199], v150 offset:1024
	ds_read_b128 v[200:203], v150 offset:2048
	ds_read_b128 v[204:207], v150 offset:3072
	ds_read_b128 v[208:211], v150 offset:4096
	ds_read_b128 v[212:215], v150 offset:5120
	ds_read_b128 v[216:219], v150 offset:6144
	ds_read_b128 v[220:223], v150 offset:7168
	global_load_lds_dwordx4 v[154:155], off
	v_lshl_add_u64 v[154:155], s[30:31], 0, v[136:137]
	s_add_i32 m0, s52, 0xe000
	s_nop 0
	global_load_lds_dwordx4 v[154:155], off
	s_waitcnt vmcnt(8)
	s_waitcnt lgkmcnt(0)
	s_barrier
	s_setprio 1
	s_waitcnt lgkmcnt(0)
	v_mfma_f32_16x16x32_bf16 v[124:127], v[160:163], v[192:195], v[124:127]
	v_mfma_f32_16x16x32_bf16 v[116:119], v[168:171], v[192:195], v[116:119]
	v_mfma_f32_16x16x32_bf16 v[108:111], v[160:163], v[200:203], v[108:111]
	v_mfma_f32_16x16x32_bf16 v[100:103], v[168:171], v[200:203], v[100:103]
	v_mfma_f32_16x16x32_bf16 v[92:95], v[160:163], v[208:211], v[92:95]
	v_mfma_f32_16x16x32_bf16 v[84:87], v[168:171], v[208:211], v[84:87]
	v_mfma_f32_16x16x32_bf16 v[76:79], v[160:163], v[216:219], v[76:79]
	v_mfma_f32_16x16x32_bf16 v[68:71], v[168:171], v[216:219], v[68:71]
	v_mfma_f32_16x16x32_bf16 v[124:127], v[164:167], v[196:199], v[124:127]
	v_mfma_f32_16x16x32_bf16 v[116:119], v[172:175], v[196:199], v[116:119]
	v_mfma_f32_16x16x32_bf16 v[108:111], v[164:167], v[204:207], v[108:111]
	v_mfma_f32_16x16x32_bf16 v[100:103], v[172:175], v[204:207], v[100:103]
	v_mfma_f32_16x16x32_bf16 v[92:95], v[164:167], v[212:215], v[92:95]
	v_mfma_f32_16x16x32_bf16 v[84:87], v[172:175], v[212:215], v[84:87]
	v_mfma_f32_16x16x32_bf16 v[76:79], v[164:167], v[220:223], v[76:79]
	v_mfma_f32_16x16x32_bf16 v[68:71], v[172:175], v[220:223], v[68:71]
	s_setprio 0
	s_setprio 1
	v_mfma_f32_16x16x32_bf16 v[120:123], v[176:179], v[192:195], v[120:123]
	v_mfma_f32_16x16x32_bf16 v[112:115], v[184:187], v[192:195], v[112:115]
	v_mfma_f32_16x16x32_bf16 v[104:107], v[176:179], v[200:203], v[104:107]
	v_mfma_f32_16x16x32_bf16 v[96:99], v[184:187], v[200:203], v[96:99]
	v_mfma_f32_16x16x32_bf16 v[88:91], v[176:179], v[208:211], v[88:91]
	v_mfma_f32_16x16x32_bf16 v[80:83], v[184:187], v[208:211], v[80:83]
	v_mfma_f32_16x16x32_bf16 v[72:75], v[176:179], v[216:219], v[72:75]
	v_mfma_f32_16x16x32_bf16 v[64:67], v[184:187], v[216:219], v[64:67]
	v_mfma_f32_16x16x32_bf16 v[120:123], v[180:183], v[196:199], v[120:123]
	v_mfma_f32_16x16x32_bf16 v[112:115], v[188:191], v[196:199], v[112:115]
	v_mfma_f32_16x16x32_bf16 v[104:107], v[180:183], v[204:207], v[104:107]
	v_mfma_f32_16x16x32_bf16 v[96:99], v[188:191], v[204:207], v[96:99]
	v_mfma_f32_16x16x32_bf16 v[88:91], v[180:183], v[212:215], v[88:91]
	v_mfma_f32_16x16x32_bf16 v[80:83], v[188:191], v[212:215], v[80:83]
	v_mfma_f32_16x16x32_bf16 v[72:75], v[180:183], v[220:223], v[72:75]
	v_mfma_f32_16x16x32_bf16 v[64:67], v[188:191], v[220:223], v[64:67]
	s_setprio 0
	s_barrier
	s_add_i32 s71, s61, s49
	v_lshl_add_u64 v[154:155], s[44:45], 0, v[132:133]
	s_mov_b32 m0, s71
	ds_read_b128 v[192:195], v150 offset:16384
	ds_read_b128 v[196:199], v150 offset:17408
	ds_read_b128 v[200:203], v150 offset:18432
	ds_read_b128 v[204:207], v150 offset:19456
	ds_read_b128 v[208:211], v150 offset:20480
	ds_read_b128 v[212:215], v150 offset:21504
	ds_read_b128 v[216:219], v150 offset:22528
	ds_read_b128 v[220:223], v150 offset:23552
	global_load_lds_dwordx4 v[154:155], off
	s_add_i32 m0, s71, 0x2000
	s_add_u32 s72, s44, 0x40000
	v_lshl_add_u64 v[224:225], s[44:45], 0, v[128:129]
	s_addc_u32 s73, s45, 0
	s_add_i32 s71, s62, s49
	global_load_lds_dwordx4 v[224:225], off
	v_lshl_add_u64 v[226:227], s[72:73], 0, v[132:133]
	s_mov_b32 m0, s71
	v_lshl_add_u64 v[228:229], s[46:47], 0, v[130:131]
	global_load_lds_dwordx4 v[226:227], off
	v_lshl_add_u64 v[226:227], s[72:73], 0, v[128:129]
	s_add_i32 m0, s71, 0x2000
	s_nop 0
	global_load_lds_dwordx4 v[226:227], off
	v_lshl_add_u64 v[226:227], s[46:47], 0, v[134:135]
	s_mov_b32 m0, s52
	s_nop 0
	global_load_lds_dwordx4 v[226:227], off
	s_mov_b32 m0, s53
	s_nop 0
	global_load_lds_dwordx4 v[228:229], off
	s_waitcnt vmcnt(8)
	s_waitcnt lgkmcnt(0)
	s_barrier
	s_setprio 1
	s_waitcnt lgkmcnt(0)
	v_mfma_f32_16x16x32_bf16 v[60:63], v[160:163], v[192:195], v[60:63]
	v_mfma_f32_16x16x32_bf16 v[52:55], v[168:171], v[192:195], v[52:55]
	v_mfma_f32_16x16x32_bf16 v[44:47], v[160:163], v[200:203], v[44:47]
	v_mfma_f32_16x16x32_bf16 v[36:39], v[168:171], v[200:203], v[36:39]
	v_mfma_f32_16x16x32_bf16 v[28:31], v[160:163], v[208:211], v[28:31]
	v_mfma_f32_16x16x32_bf16 v[20:23], v[168:171], v[208:211], v[20:23]
	v_mfma_f32_16x16x32_bf16 v[12:15], v[160:163], v[216:219], v[12:15]
	v_mfma_f32_16x16x32_bf16 v[4:7], v[168:171], v[216:219], v[4:7]
	v_mfma_f32_16x16x32_bf16 v[60:63], v[164:167], v[196:199], v[60:63]
	v_mfma_f32_16x16x32_bf16 v[52:55], v[172:175], v[196:199], v[52:55]
	v_mfma_f32_16x16x32_bf16 v[44:47], v[164:167], v[204:207], v[44:47]
	v_mfma_f32_16x16x32_bf16 v[36:39], v[172:175], v[204:207], v[36:39]
	v_mfma_f32_16x16x32_bf16 v[28:31], v[164:167], v[212:215], v[28:31]
	v_mfma_f32_16x16x32_bf16 v[20:23], v[172:175], v[212:215], v[20:23]
	v_mfma_f32_16x16x32_bf16 v[12:15], v[164:167], v[220:223], v[12:15]
	v_mfma_f32_16x16x32_bf16 v[4:7], v[172:175], v[220:223], v[4:7]
	s_setprio 0
	s_setprio 1
	v_mfma_f32_16x16x32_bf16 v[56:59], v[176:179], v[192:195], v[56:59]
	v_mfma_f32_16x16x32_bf16 v[48:51], v[184:187], v[192:195], v[48:51]
	v_mfma_f32_16x16x32_bf16 v[40:43], v[176:179], v[200:203], v[40:43]
	v_mfma_f32_16x16x32_bf16 v[32:35], v[184:187], v[200:203], v[32:35]
	v_mfma_f32_16x16x32_bf16 v[24:27], v[176:179], v[208:211], v[24:27]
	v_mfma_f32_16x16x32_bf16 v[16:19], v[184:187], v[208:211], v[16:19]
	v_mfma_f32_16x16x32_bf16 v[8:11], v[176:179], v[216:219], v[8:11]
	v_mfma_f32_16x16x32_bf16 v[0:3], v[184:187], v[216:219], v[0:3]
	v_mfma_f32_16x16x32_bf16 v[56:59], v[180:183], v[196:199], v[56:59]
	v_mfma_f32_16x16x32_bf16 v[48:51], v[188:191], v[196:199], v[48:51]
	v_mfma_f32_16x16x32_bf16 v[40:43], v[180:183], v[204:207], v[40:43]
	v_mfma_f32_16x16x32_bf16 v[32:35], v[188:191], v[204:207], v[32:35]
	v_mfma_f32_16x16x32_bf16 v[24:27], v[180:183], v[212:215], v[24:27]
	v_mfma_f32_16x16x32_bf16 v[16:19], v[188:191], v[212:215], v[16:19]
	v_mfma_f32_16x16x32_bf16 v[8:11], v[180:183], v[220:223], v[8:11]
	v_mfma_f32_16x16x32_bf16 v[0:3], v[188:191], v[220:223], v[0:3]
	s_setprio 0
	s_barrier
	s_add_i32 s71, 0, 0x18000
	v_add_u32_e32 v153, s71, v147
	s_add_i32 s72, 0, 0x1c000
	ds_read_b128 v[160:163], v153
	ds_read_b128 v[164:167], v153 offset:1024
	ds_read_b128 v[168:171], v153 offset:2048
	ds_read_b128 v[172:175], v153 offset:3072
	v_add_u32_e32 v153, s72, v147
	ds_read_b128 v[176:179], v153
	ds_read_b128 v[180:183], v153 offset:1024
	ds_read_b128 v[184:187], v153 offset:2048
	ds_read_b128 v[188:191], v153 offset:3072
	s_add_u32 s46, s46, 0x40000
	s_addc_u32 s47, s47, 0
	s_mov_b32 m0, s54
	v_lshl_add_u64 v[230:231], s[46:47], 0, v[134:135]
	ds_read_b128 v[192:195], v150 offset:32768
	ds_read_b128 v[196:199], v150 offset:33792
	ds_read_b128 v[200:203], v150 offset:34816
	ds_read_b128 v[204:207], v150 offset:35840
	ds_read_b128 v[208:211], v150 offset:36864
	ds_read_b128 v[212:215], v150 offset:37888
	ds_read_b128 v[216:219], v150 offset:38912
	ds_read_b128 v[220:223], v150 offset:39936
	global_load_lds_dwordx4 v[230:231], off
	v_lshl_add_u64 v[230:231], s[46:47], 0, v[130:131]
	s_mov_b32 m0, s55
	s_nop 0
	global_load_lds_dwordx4 v[230:231], off
	s_waitcnt vmcnt(8)
	s_waitcnt lgkmcnt(0)
	s_barrier
	s_setprio 1
	s_waitcnt lgkmcnt(0)
	v_mfma_f32_16x16x32_bf16 v[124:127], v[160:163], v[192:195], v[124:127]
	v_mfma_f32_16x16x32_bf16 v[116:119], v[168:171], v[192:195], v[116:119]
	v_mfma_f32_16x16x32_bf16 v[108:111], v[160:163], v[200:203], v[108:111]
	v_mfma_f32_16x16x32_bf16 v[100:103], v[168:171], v[200:203], v[100:103]
	v_mfma_f32_16x16x32_bf16 v[92:95], v[160:163], v[208:211], v[92:95]
	v_mfma_f32_16x16x32_bf16 v[84:87], v[168:171], v[208:211], v[84:87]
	v_mfma_f32_16x16x32_bf16 v[76:79], v[160:163], v[216:219], v[76:79]
	v_mfma_f32_16x16x32_bf16 v[68:71], v[168:171], v[216:219], v[68:71]
	v_mfma_f32_16x16x32_bf16 v[124:127], v[164:167], v[196:199], v[124:127]
	v_mfma_f32_16x16x32_bf16 v[116:119], v[172:175], v[196:199], v[116:119]
	v_mfma_f32_16x16x32_bf16 v[108:111], v[164:167], v[204:207], v[108:111]
	v_mfma_f32_16x16x32_bf16 v[100:103], v[172:175], v[204:207], v[100:103]
	v_mfma_f32_16x16x32_bf16 v[92:95], v[164:167], v[212:215], v[92:95]
	v_mfma_f32_16x16x32_bf16 v[84:87], v[172:175], v[212:215], v[84:87]
	v_mfma_f32_16x16x32_bf16 v[76:79], v[164:167], v[220:223], v[76:79]
	v_mfma_f32_16x16x32_bf16 v[68:71], v[172:175], v[220:223], v[68:71]
	s_setprio 0
	s_setprio 1
	v_mfma_f32_16x16x32_bf16 v[120:123], v[176:179], v[192:195], v[120:123]
	v_mfma_f32_16x16x32_bf16 v[112:115], v[184:187], v[192:195], v[112:115]
	v_mfma_f32_16x16x32_bf16 v[104:107], v[176:179], v[200:203], v[104:107]
	v_mfma_f32_16x16x32_bf16 v[96:99], v[184:187], v[200:203], v[96:99]
	v_mfma_f32_16x16x32_bf16 v[88:91], v[176:179], v[208:211], v[88:91]
	v_mfma_f32_16x16x32_bf16 v[80:83], v[184:187], v[208:211], v[80:83]
	v_mfma_f32_16x16x32_bf16 v[72:75], v[176:179], v[216:219], v[72:75]
	v_mfma_f32_16x16x32_bf16 v[64:67], v[184:187], v[216:219], v[64:67]
	v_mfma_f32_16x16x32_bf16 v[120:123], v[180:183], v[196:199], v[120:123]
	v_mfma_f32_16x16x32_bf16 v[112:115], v[188:191], v[196:199], v[112:115]
	v_mfma_f32_16x16x32_bf16 v[104:107], v[180:183], v[204:207], v[104:107]
	v_mfma_f32_16x16x32_bf16 v[96:99], v[188:191], v[204:207], v[96:99]
	v_mfma_f32_16x16x32_bf16 v[88:91], v[180:183], v[212:215], v[88:91]
	v_mfma_f32_16x16x32_bf16 v[80:83], v[188:191], v[212:215], v[80:83]
	v_mfma_f32_16x16x32_bf16 v[72:75], v[180:183], v[220:223], v[72:75]
	v_mfma_f32_16x16x32_bf16 v[64:67], v[188:191], v[220:223], v[64:67]
	s_setprio 0
	s_barrier
	v_add_u32_e32 v234, 0x21000, v151
	ds_read_b128 v[236:239], v234
	ds_read_b128 v[240:243], v234 offset:256
	ds_read_b128 v[244:247], v234 offset:512
	ds_read_b128 v[248:251], v234 offset:768
	v_add_u32_e32 v235, s23, v146
	v_mul_u32_u24_e32 v235, 0x1600, v235
	v_lshl_or_b32 v234, s64, 7, v149
	v_lshl_add_u32 v235, v234, 1, v235
	s_add_i32 s46, s71, s49
	v_lshl_add_u64 v[154:155], v[154:155], 0, s[14:15]
	s_mov_b32 m0, s46
	ds_read_b128 v[192:195], v150 offset:49152
	ds_read_b128 v[196:199], v150 offset:50176
	ds_read_b128 v[200:203], v150 offset:51200
	ds_read_b128 v[204:207], v150 offset:52224
	ds_read_b128 v[208:211], v150 offset:53248
	ds_read_b128 v[212:215], v150 offset:54272
	ds_read_b128 v[216:219], v150 offset:55296
	ds_read_b128 v[220:223], v150 offset:56320
	global_load_lds_dwordx4 v[154:155], off
	s_add_i32 m0, s46, 0x2000
	s_add_u32 s44, s44, 0x40080
	v_lshl_add_u64 v[154:155], v[224:225], 0, s[14:15]
	s_addc_u32 s45, s45, 0
	s_add_i32 s46, s72, s49
	global_load_lds_dwordx4 v[154:155], off
	v_lshl_add_u64 v[154:155], s[44:45], 0, v[132:133]
	s_mov_b32 m0, s46
	s_nop 0
	global_load_lds_dwordx4 v[154:155], off
	v_lshl_add_u64 v[154:155], s[44:45], 0, v[128:129]
	s_add_i32 m0, s46, 0x2000
	s_nop 0
	global_load_lds_dwordx4 v[154:155], off
	v_lshl_add_u64 v[154:155], v[226:227], 0, s[14:15]
	s_mov_b32 m0, s57
	s_nop 0
	global_load_lds_dwordx4 v[154:155], off
	v_lshl_add_u64 v[154:155], v[228:229], 0, s[14:15]
	s_mov_b32 m0, s58
	s_nop 0
	global_load_lds_dwordx4 v[154:155], off
	s_waitcnt lgkmcnt(8)
	v_add_f32_e32 v236, v236, v237
	v_add_f32_e32 v238, v238, v239
	v_add_f32_e32 v240, v240, v241
	v_add_f32_e32 v242, v242, v243
	v_add_f32_e32 v244, v244, v245
	v_add_f32_e32 v246, v246, v247
	v_add_f32_e32 v248, v248, v249
	v_add_f32_e32 v250, v250, v251
	v_add_f32_e32 v236, v236, v238
	v_add_f32_e32 v240, v240, v242
	v_add_f32_e32 v244, v244, v246
	v_add_f32_e32 v248, v248, v250
	v_fmamk_f32 v236, v236, 0x3a800000, v152
	v_fmamk_f32 v240, v240, 0x3a800000, v152
	v_fmamk_f32 v244, v244, 0x3a800000, v152
	v_fmamk_f32 v248, v248, 0x3a800000, v152
	v_rsq_f32_e32 v236, v236
	v_rsq_f32_e32 v240, v240
	v_rsq_f32_e32 v244, v244
	v_rsq_f32_e32 v248, v248
	v_mul_f32_e32 v252, 0xbfb8aa3b, v236
	v_mul_f32_e32 v254, v236, v236
	v_pk_mul_f32 v[120:121], v[124:125], v[120:121]
	v_pk_mul_f32 v[122:123], v[126:127], v[122:123]
	v_pk_mul_f32 v[112:113], v[116:117], v[112:113]
	v_pk_mul_f32 v[114:115], v[118:119], v[114:115]
	v_pk_mul_f32 v[124:125], v[124:125], v[252:253] op_sel_hi:[1,0]
	v_pk_mul_f32 v[126:127], v[126:127], v[252:253] op_sel_hi:[1,0]
	v_pk_mul_f32 v[116:117], v[116:117], v[252:253] op_sel_hi:[1,0]
	v_pk_mul_f32 v[118:119], v[118:119], v[252:253] op_sel_hi:[1,0]
	v_exp_f32_e32 v124, v124
	v_exp_f32_e32 v125, v125
	v_exp_f32_e32 v126, v126
	v_exp_f32_e32 v127, v127
	v_exp_f32_e32 v116, v116
	v_exp_f32_e32 v117, v117
	v_exp_f32_e32 v118, v118
	v_exp_f32_e32 v119, v119
	v_pk_add_f32 v[124:125], v[124:125], 1.0 op_sel_hi:[1,0]
	v_pk_add_f32 v[126:127], v[126:127], 1.0 op_sel_hi:[1,0]
	v_pk_add_f32 v[116:117], v[116:117], 1.0 op_sel_hi:[1,0]
	v_pk_add_f32 v[118:119], v[118:119], 1.0 op_sel_hi:[1,0]
	v_rcp_f32_e32 v124, v124
	v_rcp_f32_e32 v125, v125
	v_rcp_f32_e32 v126, v126
	v_rcp_f32_e32 v127, v127
	v_rcp_f32_e32 v116, v116
	v_rcp_f32_e32 v117, v117
	v_rcp_f32_e32 v118, v118
	v_rcp_f32_e32 v119, v119
	v_pk_mul_f32 v[120:121], v[120:121], v[254:255] op_sel_hi:[1,0]
	v_pk_mul_f32 v[122:123], v[122:123], v[254:255] op_sel_hi:[1,0]
	v_pk_mul_f32 v[112:113], v[112:113], v[254:255] op_sel_hi:[1,0]
	v_pk_mul_f32 v[114:115], v[114:115], v[254:255] op_sel_hi:[1,0]
	v_pk_mul_f32 v[120:121], v[120:121], v[124:125]
	v_pk_mul_f32 v[122:123], v[122:123], v[126:127]
	v_pk_mul_f32 v[112:113], v[112:113], v[116:117]
	v_pk_mul_f32 v[114:115], v[114:115], v[118:119]
	v_cvt_pk_bf16_f32 v120, v120, v121
	v_cvt_pk_bf16_f32 v121, v122, v123
	v_cvt_pk_bf16_f32 v122, v112, v113
	v_cvt_pk_bf16_f32 v123, v114, v115
	global_store_dwordx4 v235, v[120:123], s[10:11]
	v_add_u32_e32 v234, 0x16000, v235
	v_mul_f32_e32 v252, 0xbfb8aa3b, v240
	v_mul_f32_e32 v254, v240, v240
	v_pk_mul_f32 v[104:105], v[108:109], v[104:105]
	v_pk_mul_f32 v[106:107], v[110:111], v[106:107]
	v_pk_mul_f32 v[96:97], v[100:101], v[96:97]
	v_pk_mul_f32 v[98:99], v[102:103], v[98:99]
	v_pk_mul_f32 v[108:109], v[108:109], v[252:253] op_sel_hi:[1,0]
	v_pk_mul_f32 v[110:111], v[110:111], v[252:253] op_sel_hi:[1,0]
	v_pk_mul_f32 v[100:101], v[100:101], v[252:253] op_sel_hi:[1,0]
	v_pk_mul_f32 v[102:103], v[102:103], v[252:253] op_sel_hi:[1,0]
	v_exp_f32_e32 v108, v108
	v_exp_f32_e32 v109, v109
	v_exp_f32_e32 v110, v110
	v_exp_f32_e32 v111, v111
	v_exp_f32_e32 v100, v100
	v_exp_f32_e32 v101, v101
	v_exp_f32_e32 v102, v102
	v_exp_f32_e32 v103, v103
	v_pk_add_f32 v[108:109], v[108:109], 1.0 op_sel_hi:[1,0]
	v_pk_add_f32 v[110:111], v[110:111], 1.0 op_sel_hi:[1,0]
	v_pk_add_f32 v[100:101], v[100:101], 1.0 op_sel_hi:[1,0]
	v_pk_add_f32 v[102:103], v[102:103], 1.0 op_sel_hi:[1,0]
	v_rcp_f32_e32 v108, v108
	v_rcp_f32_e32 v109, v109
	v_rcp_f32_e32 v110, v110
	v_rcp_f32_e32 v111, v111
	v_rcp_f32_e32 v100, v100
	v_rcp_f32_e32 v101, v101
	v_rcp_f32_e32 v102, v102
	v_rcp_f32_e32 v103, v103
	v_pk_mul_f32 v[104:105], v[104:105], v[254:255] op_sel_hi:[1,0]
	v_pk_mul_f32 v[106:107], v[106:107], v[254:255] op_sel_hi:[1,0]
	v_pk_mul_f32 v[96:97], v[96:97], v[254:255] op_sel_hi:[1,0]
	v_pk_mul_f32 v[98:99], v[98:99], v[254:255] op_sel_hi:[1,0]
	v_pk_mul_f32 v[104:105], v[104:105], v[108:109]
	v_pk_mul_f32 v[106:107], v[106:107], v[110:111]
	v_pk_mul_f32 v[96:97], v[96:97], v[100:101]
	v_pk_mul_f32 v[98:99], v[98:99], v[102:103]
	v_cvt_pk_bf16_f32 v104, v104, v105
	v_cvt_pk_bf16_f32 v105, v106, v107
	v_cvt_pk_bf16_f32 v106, v96, v97
	v_cvt_pk_bf16_f32 v107, v98, v99
	global_store_dwordx4 v234, v[104:107], s[10:11]
	v_add_u32_e32 v235, 0x16000, v234
	v_mul_f32_e32 v252, 0xbfb8aa3b, v244
	v_mul_f32_e32 v254, v244, v244
	v_pk_mul_f32 v[88:89], v[92:93], v[88:89]
	v_pk_mul_f32 v[90:91], v[94:95], v[90:91]
	v_pk_mul_f32 v[80:81], v[84:85], v[80:81]
	v_pk_mul_f32 v[82:83], v[86:87], v[82:83]
	v_pk_mul_f32 v[92:93], v[92:93], v[252:253] op_sel_hi:[1,0]
	v_pk_mul_f32 v[94:95], v[94:95], v[252:253] op_sel_hi:[1,0]
	v_pk_mul_f32 v[84:85], v[84:85], v[252:253] op_sel_hi:[1,0]
	v_pk_mul_f32 v[86:87], v[86:87], v[252:253] op_sel_hi:[1,0]
	v_exp_f32_e32 v92, v92
	v_exp_f32_e32 v93, v93
	v_exp_f32_e32 v94, v94
	v_exp_f32_e32 v95, v95
	v_exp_f32_e32 v84, v84
	v_exp_f32_e32 v85, v85
	v_exp_f32_e32 v86, v86
	v_exp_f32_e32 v87, v87
	v_pk_add_f32 v[92:93], v[92:93], 1.0 op_sel_hi:[1,0]
	v_pk_add_f32 v[94:95], v[94:95], 1.0 op_sel_hi:[1,0]
	v_pk_add_f32 v[84:85], v[84:85], 1.0 op_sel_hi:[1,0]
	v_pk_add_f32 v[86:87], v[86:87], 1.0 op_sel_hi:[1,0]
	v_rcp_f32_e32 v92, v92
	v_rcp_f32_e32 v93, v93
	v_rcp_f32_e32 v94, v94
	v_rcp_f32_e32 v95, v95
	v_rcp_f32_e32 v84, v84
	v_rcp_f32_e32 v85, v85
	v_rcp_f32_e32 v86, v86
	v_rcp_f32_e32 v87, v87
	v_pk_mul_f32 v[88:89], v[88:89], v[254:255] op_sel_hi:[1,0]
	v_pk_mul_f32 v[90:91], v[90:91], v[254:255] op_sel_hi:[1,0]
	v_pk_mul_f32 v[80:81], v[80:81], v[254:255] op_sel_hi:[1,0]
	v_pk_mul_f32 v[82:83], v[82:83], v[254:255] op_sel_hi:[1,0]
	v_pk_mul_f32 v[88:89], v[88:89], v[92:93]
	v_pk_mul_f32 v[90:91], v[90:91], v[94:95]
	v_pk_mul_f32 v[80:81], v[80:81], v[84:85]
	v_pk_mul_f32 v[82:83], v[82:83], v[86:87]
	v_cvt_pk_bf16_f32 v88, v88, v89
	v_cvt_pk_bf16_f32 v89, v90, v91
	v_cvt_pk_bf16_f32 v90, v80, v81
	v_cvt_pk_bf16_f32 v91, v82, v83
	global_store_dwordx4 v235, v[88:91], s[10:11]
	v_add_u32_e32 v234, 0x16000, v235
	v_mul_f32_e32 v252, 0xbfb8aa3b, v248
	v_mul_f32_e32 v254, v248, v248
	v_pk_mul_f32 v[72:73], v[76:77], v[72:73]
	v_pk_mul_f32 v[74:75], v[78:79], v[74:75]
	v_pk_mul_f32 v[64:65], v[68:69], v[64:65]
	v_pk_mul_f32 v[66:67], v[70:71], v[66:67]
	v_pk_mul_f32 v[76:77], v[76:77], v[252:253] op_sel_hi:[1,0]
	v_pk_mul_f32 v[78:79], v[78:79], v[252:253] op_sel_hi:[1,0]
	v_pk_mul_f32 v[68:69], v[68:69], v[252:253] op_sel_hi:[1,0]
	v_pk_mul_f32 v[70:71], v[70:71], v[252:253] op_sel_hi:[1,0]
	v_exp_f32_e32 v76, v76
	v_exp_f32_e32 v77, v77
	v_exp_f32_e32 v78, v78
	v_exp_f32_e32 v79, v79
	v_exp_f32_e32 v68, v68
	v_exp_f32_e32 v69, v69
	v_exp_f32_e32 v70, v70
	v_exp_f32_e32 v71, v71
	v_pk_add_f32 v[76:77], v[76:77], 1.0 op_sel_hi:[1,0]
	v_pk_add_f32 v[78:79], v[78:79], 1.0 op_sel_hi:[1,0]
	v_pk_add_f32 v[68:69], v[68:69], 1.0 op_sel_hi:[1,0]
	v_pk_add_f32 v[70:71], v[70:71], 1.0 op_sel_hi:[1,0]
	v_rcp_f32_e32 v76, v76
	v_rcp_f32_e32 v77, v77
	v_rcp_f32_e32 v78, v78
	v_rcp_f32_e32 v79, v79
	v_rcp_f32_e32 v68, v68
	v_rcp_f32_e32 v69, v69
	v_rcp_f32_e32 v70, v70
	v_rcp_f32_e32 v71, v71
	v_pk_mul_f32 v[72:73], v[72:73], v[254:255] op_sel_hi:[1,0]
	v_pk_mul_f32 v[74:75], v[74:75], v[254:255] op_sel_hi:[1,0]
	v_pk_mul_f32 v[64:65], v[64:65], v[254:255] op_sel_hi:[1,0]
	v_pk_mul_f32 v[66:67], v[66:67], v[254:255] op_sel_hi:[1,0]
	v_pk_mul_f32 v[72:73], v[72:73], v[76:77]
	v_pk_mul_f32 v[74:75], v[74:75], v[78:79]
	v_pk_mul_f32 v[64:65], v[64:65], v[68:69]
	v_pk_mul_f32 v[66:67], v[66:67], v[70:71]
	v_cvt_pk_bf16_f32 v72, v72, v73
	v_cvt_pk_bf16_f32 v73, v74, v75
	v_cvt_pk_bf16_f32 v74, v64, v65
	v_cvt_pk_bf16_f32 v75, v66, v67
	global_store_dwordx4 v234, v[72:75], s[10:11]
	s_waitcnt vmcnt(12)
	s_waitcnt lgkmcnt(0)
	s_barrier
	s_setprio 1
	s_waitcnt lgkmcnt(0)
	v_mfma_f32_16x16x32_bf16 v[60:63], v[160:163], v[192:195], v[60:63]
	v_mfma_f32_16x16x32_bf16 v[52:55], v[168:171], v[192:195], v[52:55]
	v_mfma_f32_16x16x32_bf16 v[44:47], v[160:163], v[200:203], v[44:47]
	v_mfma_f32_16x16x32_bf16 v[36:39], v[168:171], v[200:203], v[36:39]
	v_mfma_f32_16x16x32_bf16 v[28:31], v[160:163], v[208:211], v[28:31]
	v_mfma_f32_16x16x32_bf16 v[20:23], v[168:171], v[208:211], v[20:23]
	v_mfma_f32_16x16x32_bf16 v[12:15], v[160:163], v[216:219], v[12:15]
	v_mfma_f32_16x16x32_bf16 v[4:7], v[168:171], v[216:219], v[4:7]
	v_mfma_f32_16x16x32_bf16 v[60:63], v[164:167], v[196:199], v[60:63]
	v_mfma_f32_16x16x32_bf16 v[52:55], v[172:175], v[196:199], v[52:55]
	v_mfma_f32_16x16x32_bf16 v[44:47], v[164:167], v[204:207], v[44:47]
	v_mfma_f32_16x16x32_bf16 v[36:39], v[172:175], v[204:207], v[36:39]
	v_mfma_f32_16x16x32_bf16 v[28:31], v[164:167], v[212:215], v[28:31]
	v_mfma_f32_16x16x32_bf16 v[20:23], v[172:175], v[212:215], v[20:23]
	v_mfma_f32_16x16x32_bf16 v[12:15], v[164:167], v[220:223], v[12:15]
	v_mfma_f32_16x16x32_bf16 v[4:7], v[172:175], v[220:223], v[4:7]
	s_setprio 0
	s_setprio 1
	v_mfma_f32_16x16x32_bf16 v[56:59], v[176:179], v[192:195], v[56:59]
	v_mfma_f32_16x16x32_bf16 v[48:51], v[184:187], v[192:195], v[48:51]
	v_mfma_f32_16x16x32_bf16 v[40:43], v[176:179], v[200:203], v[40:43]
	v_mfma_f32_16x16x32_bf16 v[32:35], v[184:187], v[200:203], v[32:35]
	v_mfma_f32_16x16x32_bf16 v[24:27], v[176:179], v[208:211], v[24:27]
	v_mfma_f32_16x16x32_bf16 v[16:19], v[184:187], v[208:211], v[16:19]
	v_mfma_f32_16x16x32_bf16 v[8:11], v[176:179], v[216:219], v[8:11]
	v_mfma_f32_16x16x32_bf16 v[0:3], v[184:187], v[216:219], v[0:3]
	v_mfma_f32_16x16x32_bf16 v[56:59], v[180:183], v[196:199], v[56:59]
	v_mfma_f32_16x16x32_bf16 v[48:51], v[188:191], v[196:199], v[48:51]
	v_mfma_f32_16x16x32_bf16 v[40:43], v[180:183], v[204:207], v[40:43]
	v_mfma_f32_16x16x32_bf16 v[32:35], v[188:191], v[204:207], v[32:35]
	v_mfma_f32_16x16x32_bf16 v[24:27], v[180:183], v[212:215], v[24:27]
	v_mfma_f32_16x16x32_bf16 v[16:19], v[188:191], v[212:215], v[16:19]
	v_mfma_f32_16x16x32_bf16 v[8:11], v[180:183], v[220:223], v[8:11]
	v_mfma_f32_16x16x32_bf16 v[0:3], v[188:191], v[220:223], v[0:3]
	s_setprio 0
	s_barrier
	s_add_i32 s70, s70, 2
	s_add_u32 s68, s68, 0x100
	s_addc_u32 s69, s69, 0
	s_add_u32 s30, s30, 0x100
	s_addc_u32 s31, s31, 0

.LBB0_1102:
	v_add_u32_e32 v235, 0x84000, v235
	v_add_u32_e32 v234, 0x21800, v151
	ds_read_b128 v[236:239], v234
	ds_read_b128 v[240:243], v234 offset:256
	ds_read_b128 v[244:247], v234 offset:512
	ds_read_b128 v[248:251], v234 offset:768
	s_waitcnt lgkmcnt(0)
	v_add_f32_e32 v236, v236, v237
	v_add_f32_e32 v238, v238, v239
	v_add_f32_e32 v240, v240, v241
	v_add_f32_e32 v242, v242, v243
	v_add_f32_e32 v244, v244, v245
	v_add_f32_e32 v246, v246, v247
	v_add_f32_e32 v248, v248, v249
	v_add_f32_e32 v250, v250, v251
	v_add_f32_e32 v236, v236, v238
	v_add_f32_e32 v240, v240, v242
	v_add_f32_e32 v244, v244, v246
	v_add_f32_e32 v248, v248, v250
	v_fmamk_f32 v236, v236, 0x3a800000, v152
	v_fmamk_f32 v240, v240, 0x3a800000, v152
	v_fmamk_f32 v244, v244, 0x3a800000, v152
	v_fmamk_f32 v248, v248, 0x3a800000, v152
	v_rsq_f32_e32 v236, v236
	v_rsq_f32_e32 v240, v240
	v_rsq_f32_e32 v244, v244
	v_rsq_f32_e32 v248, v248
	v_mul_f32_e32 v252, 0xbfb8aa3b, v236
	v_mul_f32_e32 v254, v236, v236
	v_pk_mul_f32 v[56:57], v[60:61], v[56:57]
	v_pk_mul_f32 v[58:59], v[62:63], v[58:59]
	v_pk_mul_f32 v[48:49], v[52:53], v[48:49]
	v_pk_mul_f32 v[50:51], v[54:55], v[50:51]
	v_pk_mul_f32 v[60:61], v[60:61], v[252:253] op_sel_hi:[1,0]
	v_pk_mul_f32 v[62:63], v[62:63], v[252:253] op_sel_hi:[1,0]
	v_pk_mul_f32 v[52:53], v[52:53], v[252:253] op_sel_hi:[1,0]
	v_pk_mul_f32 v[54:55], v[54:55], v[252:253] op_sel_hi:[1,0]
	v_exp_f32_e32 v60, v60
	v_exp_f32_e32 v61, v61
	v_exp_f32_e32 v62, v62
	v_exp_f32_e32 v63, v63
	v_exp_f32_e32 v52, v52
	v_exp_f32_e32 v53, v53
	v_exp_f32_e32 v54, v54
	v_exp_f32_e32 v55, v55
	v_pk_add_f32 v[60:61], v[60:61], 1.0 op_sel_hi:[1,0]
	v_pk_add_f32 v[62:63], v[62:63], 1.0 op_sel_hi:[1,0]
	v_pk_add_f32 v[52:53], v[52:53], 1.0 op_sel_hi:[1,0]
	v_pk_add_f32 v[54:55], v[54:55], 1.0 op_sel_hi:[1,0]
	v_rcp_f32_e32 v60, v60
	v_rcp_f32_e32 v61, v61
	v_rcp_f32_e32 v62, v62
	v_rcp_f32_e32 v63, v63
	v_rcp_f32_e32 v52, v52
	v_rcp_f32_e32 v53, v53
	v_rcp_f32_e32 v54, v54
	v_rcp_f32_e32 v55, v55
	v_pk_mul_f32 v[56:57], v[56:57], v[254:255] op_sel_hi:[1,0]
	v_pk_mul_f32 v[58:59], v[58:59], v[254:255] op_sel_hi:[1,0]
	v_pk_mul_f32 v[48:49], v[48:49], v[254:255] op_sel_hi:[1,0]
	v_pk_mul_f32 v[50:51], v[50:51], v[254:255] op_sel_hi:[1,0]
	v_pk_mul_f32 v[56:57], v[56:57], v[60:61]
	v_pk_mul_f32 v[58:59], v[58:59], v[62:63]
	v_pk_mul_f32 v[48:49], v[48:49], v[52:53]
	v_pk_mul_f32 v[50:51], v[50:51], v[54:55]
	v_cvt_pk_bf16_f32 v56, v56, v57
	v_cvt_pk_bf16_f32 v57, v58, v59
	v_cvt_pk_bf16_f32 v58, v48, v49
	v_cvt_pk_bf16_f32 v59, v50, v51
	global_store_dwordx4 v235, v[56:59], s[10:11]
	v_add_u32_e32 v234, 0x16000, v235
	v_mul_f32_e32 v252, 0xbfb8aa3b, v240
	v_mul_f32_e32 v254, v240, v240
	v_pk_mul_f32 v[40:41], v[44:45], v[40:41]
	v_pk_mul_f32 v[42:43], v[46:47], v[42:43]
	v_pk_mul_f32 v[32:33], v[36:37], v[32:33]
	v_pk_mul_f32 v[34:35], v[38:39], v[34:35]
	v_pk_mul_f32 v[44:45], v[44:45], v[252:253] op_sel_hi:[1,0]
	v_pk_mul_f32 v[46:47], v[46:47], v[252:253] op_sel_hi:[1,0]
	v_pk_mul_f32 v[36:37], v[36:37], v[252:253] op_sel_hi:[1,0]
	v_pk_mul_f32 v[38:39], v[38:39], v[252:253] op_sel_hi:[1,0]
	v_exp_f32_e32 v44, v44
	v_exp_f32_e32 v45, v45
	v_exp_f32_e32 v46, v46
	v_exp_f32_e32 v47, v47
	v_exp_f32_e32 v36, v36
	v_exp_f32_e32 v37, v37
	v_exp_f32_e32 v38, v38
	v_exp_f32_e32 v39, v39
	v_pk_add_f32 v[44:45], v[44:45], 1.0 op_sel_hi:[1,0]
	v_pk_add_f32 v[46:47], v[46:47], 1.0 op_sel_hi:[1,0]
	v_pk_add_f32 v[36:37], v[36:37], 1.0 op_sel_hi:[1,0]
	v_pk_add_f32 v[38:39], v[38:39], 1.0 op_sel_hi:[1,0]
	v_rcp_f32_e32 v44, v44
	v_rcp_f32_e32 v45, v45
	v_rcp_f32_e32 v46, v46
	v_rcp_f32_e32 v47, v47
	v_rcp_f32_e32 v36, v36
	v_rcp_f32_e32 v37, v37
	v_rcp_f32_e32 v38, v38
	v_rcp_f32_e32 v39, v39
	v_pk_mul_f32 v[40:41], v[40:41], v[254:255] op_sel_hi:[1,0]
	v_pk_mul_f32 v[42:43], v[42:43], v[254:255] op_sel_hi:[1,0]
	v_pk_mul_f32 v[32:33], v[32:33], v[254:255] op_sel_hi:[1,0]
	v_pk_mul_f32 v[34:35], v[34:35], v[254:255] op_sel_hi:[1,0]
	v_pk_mul_f32 v[40:41], v[40:41], v[44:45]
	v_pk_mul_f32 v[42:43], v[42:43], v[46:47]
	v_pk_mul_f32 v[32:33], v[32:33], v[36:37]
	v_pk_mul_f32 v[34:35], v[34:35], v[38:39]
	v_cvt_pk_bf16_f32 v40, v40, v41
	v_cvt_pk_bf16_f32 v41, v42, v43
	v_cvt_pk_bf16_f32 v42, v32, v33
	v_cvt_pk_bf16_f32 v43, v34, v35
	global_store_dwordx4 v234, v[40:43], s[10:11]
	v_add_u32_e32 v235, 0x16000, v234
	v_mul_f32_e32 v252, 0xbfb8aa3b, v244
	v_mul_f32_e32 v254, v244, v244
	v_pk_mul_f32 v[24:25], v[28:29], v[24:25]
	v_pk_mul_f32 v[26:27], v[30:31], v[26:27]
	v_pk_mul_f32 v[16:17], v[20:21], v[16:17]
	v_pk_mul_f32 v[18:19], v[22:23], v[18:19]
	v_pk_mul_f32 v[28:29], v[28:29], v[252:253] op_sel_hi:[1,0]
	v_pk_mul_f32 v[30:31], v[30:31], v[252:253] op_sel_hi:[1,0]
	v_pk_mul_f32 v[20:21], v[20:21], v[252:253] op_sel_hi:[1,0]
	v_pk_mul_f32 v[22:23], v[22:23], v[252:253] op_sel_hi:[1,0]
	v_exp_f32_e32 v28, v28
	v_exp_f32_e32 v29, v29
	v_exp_f32_e32 v30, v30
	v_exp_f32_e32 v31, v31
	v_exp_f32_e32 v20, v20
	v_exp_f32_e32 v21, v21
	v_exp_f32_e32 v22, v22
	v_exp_f32_e32 v23, v23
	v_pk_add_f32 v[28:29], v[28:29], 1.0 op_sel_hi:[1,0]
	v_pk_add_f32 v[30:31], v[30:31], 1.0 op_sel_hi:[1,0]
	v_pk_add_f32 v[20:21], v[20:21], 1.0 op_sel_hi:[1,0]
	v_pk_add_f32 v[22:23], v[22:23], 1.0 op_sel_hi:[1,0]
	v_rcp_f32_e32 v28, v28
	v_rcp_f32_e32 v29, v29
	v_rcp_f32_e32 v30, v30
	v_rcp_f32_e32 v31, v31
	v_rcp_f32_e32 v20, v20
	v_rcp_f32_e32 v21, v21
	v_rcp_f32_e32 v22, v22
	v_rcp_f32_e32 v23, v23
	v_pk_mul_f32 v[24:25], v[24:25], v[254:255] op_sel_hi:[1,0]
	v_pk_mul_f32 v[26:27], v[26:27], v[254:255] op_sel_hi:[1,0]
	v_pk_mul_f32 v[16:17], v[16:17], v[254:255] op_sel_hi:[1,0]
	v_pk_mul_f32 v[18:19], v[18:19], v[254:255] op_sel_hi:[1,0]
	v_pk_mul_f32 v[24:25], v[24:25], v[28:29]
	v_pk_mul_f32 v[26:27], v[26:27], v[30:31]
	v_pk_mul_f32 v[16:17], v[16:17], v[20:21]
	v_pk_mul_f32 v[18:19], v[18:19], v[22:23]
	v_cvt_pk_bf16_f32 v24, v24, v25
	v_cvt_pk_bf16_f32 v25, v26, v27
	v_cvt_pk_bf16_f32 v26, v16, v17
	v_cvt_pk_bf16_f32 v27, v18, v19
	global_store_dwordx4 v235, v[24:27], s[10:11]
	v_add_u32_e32 v234, 0x16000, v235
	v_mul_f32_e32 v252, 0xbfb8aa3b, v248
	v_mul_f32_e32 v254, v248, v248
	v_pk_mul_f32 v[8:9], v[12:13], v[8:9]
	v_pk_mul_f32 v[10:11], v[14:15], v[10:11]
	v_pk_mul_f32 v[0:1], v[4:5], v[0:1]
	v_pk_mul_f32 v[2:3], v[6:7], v[2:3]
	v_pk_mul_f32 v[12:13], v[12:13], v[252:253] op_sel_hi:[1,0]
	v_pk_mul_f32 v[14:15], v[14:15], v[252:253] op_sel_hi:[1,0]
	v_pk_mul_f32 v[4:5], v[4:5], v[252:253] op_sel_hi:[1,0]
	v_pk_mul_f32 v[6:7], v[6:7], v[252:253] op_sel_hi:[1,0]
	v_exp_f32_e32 v12, v12
	v_exp_f32_e32 v13, v13
	v_exp_f32_e32 v14, v14
	v_exp_f32_e32 v15, v15
	v_exp_f32_e32 v4, v4
	v_exp_f32_e32 v5, v5
	v_exp_f32_e32 v6, v6
	v_exp_f32_e32 v7, v7
	v_pk_add_f32 v[12:13], v[12:13], 1.0 op_sel_hi:[1,0]
	v_pk_add_f32 v[14:15], v[14:15], 1.0 op_sel_hi:[1,0]
	v_pk_add_f32 v[4:5], v[4:5], 1.0 op_sel_hi:[1,0]
	v_pk_add_f32 v[6:7], v[6:7], 1.0 op_sel_hi:[1,0]
	v_rcp_f32_e32 v12, v12
	v_rcp_f32_e32 v13, v13
	v_rcp_f32_e32 v14, v14
	v_rcp_f32_e32 v15, v15
	v_rcp_f32_e32 v4, v4
	v_rcp_f32_e32 v5, v5
	v_rcp_f32_e32 v6, v6
	v_rcp_f32_e32 v7, v7
	v_pk_mul_f32 v[8:9], v[8:9], v[254:255] op_sel_hi:[1,0]
	v_pk_mul_f32 v[10:11], v[10:11], v[254:255] op_sel_hi:[1,0]
	v_pk_mul_f32 v[0:1], v[0:1], v[254:255] op_sel_hi:[1,0]
	v_pk_mul_f32 v[2:3], v[2:3], v[254:255] op_sel_hi:[1,0]
	v_pk_mul_f32 v[8:9], v[8:9], v[12:13]
	v_pk_mul_f32 v[10:11], v[10:11], v[14:15]
	v_pk_mul_f32 v[0:1], v[0:1], v[4:5]
	v_pk_mul_f32 v[2:3], v[2:3], v[6:7]
	v_cvt_pk_bf16_f32 v8, v8, v9
	v_cvt_pk_bf16_f32 v9, v10, v11
	v_cvt_pk_bf16_f32 v10, v0, v1
	v_cvt_pk_bf16_f32 v11, v2, v3
	global_store_dwordx4 v234, v[8:11], s[10:11]
	s_andn2_b64 vcc, exec, s[6:7]
	s_mov_b64 s[6:7], -1
	s_cbranch_vccnz .LBB0_1093
	s_andn2_b64 vcc, exec, s[8:9]
	s_cbranch_vccnz .LBB0_1092
	s_barrier
	s_branch .LBB0_1092

	.amdhsa_kernel _ZN2mk14fwd_megakernelILi0ELi16EEEvNS_4ArgsE
		.amdhsa_group_segment_fixed_size 0
		.amdhsa_private_segment_fixed_size 0
		.amdhsa_kernarg_size 392
		.amdhsa_user_sgpr_count 2
		.amdhsa_user_sgpr_dispatch_ptr 0
		.amdhsa_user_sgpr_queue_ptr 0
		.amdhsa_user_sgpr_kernarg_segment_ptr 1
		.amdhsa_user_sgpr_dispatch_id 0
		.amdhsa_user_sgpr_kernarg_preload_length 0
		.amdhsa_user_sgpr_kernarg_preload_offset 0
		.amdhsa_user_sgpr_private_segment_size 0
		.amdhsa_uses_dynamic_stack 0
		.amdhsa_enable_private_segment 0
		.amdhsa_system_sgpr_workgroup_id_x 1
		.amdhsa_system_sgpr_workgroup_id_y 0
		.amdhsa_system_sgpr_workgroup_id_z 0
		.amdhsa_system_sgpr_workgroup_info 0
		.amdhsa_system_vgpr_workitem_id 2
		.amdhsa_next_free_vgpr 256
		.amdhsa_next_free_sgpr 98
		.amdhsa_accum_offset 256
		.amdhsa_reserve_vcc 1
		.amdhsa_float_round_mode_32 0
		.amdhsa_float_round_mode_16_64 0
		.amdhsa_float_denorm_mode_32 3
		.amdhsa_float_denorm_mode_16_64 3
		.amdhsa_dx10_clamp 1
		.amdhsa_ieee_mode 1
		.amdhsa_fp16_overflow 0
		.amdhsa_tg_split 0
		.amdhsa_exception_fp_ieee_invalid_op 0
		.amdhsa_exception_fp_denorm_src 0
		.amdhsa_exception_fp_ieee_div_zero 0
		.amdhsa_exception_fp_ieee_overflow 0
		.amdhsa_exception_fp_ieee_underflow 0
		.amdhsa_exception_fp_ieee_inexact 0
		.amdhsa_exception_int_div_zero 0
	.end_amdhsa_kernel

amdhsa.kernels:
  - .agpr_count:     0
    .args:
      - .offset:         0
        .size:           136
        .value_kind:     by_value
      - .offset:         136
        .size:           4
        .value_kind:     hidden_block_count_x
      - .offset:         140
        .size:           4
        .value_kind:     hidden_block_count_y
      - .offset:         144
        .size:           4
        .value_kind:     hidden_block_count_z
      - .offset:         148
        .size:           2
        .value_kind:     hidden_group_size_x
      - .offset:         150
        .size:           2
        .value_kind:     hidden_group_size_y
      - .offset:         152
        .size:           2
        .value_kind:     hidden_group_size_z
      - .offset:         154
        .size:           2
        .value_kind:     hidden_remainder_x
      - .offset:         156
        .size:           2
        .value_kind:     hidden_remainder_y
      - .offset:         158
        .size:           2
        .value_kind:     hidden_remainder_z
      - .offset:         176
        .size:           8
        .value_kind:     hidden_global_offset_x
      - .offset:         184
        .size:           8
        .value_kind:     hidden_global_offset_y
      - .offset:         192
        .size:           8
        .value_kind:     hidden_global_offset_z
      - .offset:         200
        .size:           2
        .value_kind:     hidden_grid_dims
      - .offset:         224
        .size:           8
        .value_kind:     hidden_multigrid_sync_arg
      - .offset:         256
        .size:           4
        .value_kind:     hidden_dynamic_lds_size
    .group_segment_fixed_size: 0
    .kernarg_segment_align: 8
    .kernarg_segment_size: 392
    .language:       OpenCL C
    .language_version:
      - 2
      - 0
    .max_flat_workgroup_size: 512
    .name:           _ZN2mk14fwd_megakernelILi0ELi16EEEvNS_4ArgsE
    .private_segment_fixed_size: 0
    .sgpr_count:     104
    .sgpr_spill_count: 0
    .symbol:         _ZN2mk14fwd_megakernelILi0ELi16EEEvNS_4ArgsE.kd
    .uniform_work_group_size: 1
    .uses_dynamic_stack: false
    .vgpr_count:     256
    .vgpr_spill_count: 0
    .wavefront_size: 64
